# NA: cross-half max combine moved from the per-tile common path into the rescale path (branch on own-half maxima)
# speedup vs baseline: 1.0066x; 1.0066x over previous
.Lna_wloop:
	s_sub_i32 s36, s24, s23
	s_cmp_lt_u32 s36, s63
	s_cselect_b64 s[40:41], -1, 0
	s_add_i32 s36, s36, 1
	s_cmp_lt_u32 s36, 8
	s_cselect_b64 s[44:45], -1, 0
	s_sub_i32 s37, s36, s62
	s_cmp_lt_u32 s37, 8
	s_cselect_b64 s[46:47], -1, 0
	s_and_b64 s[48:49], s[44:45], s[64:65]
	s_andn2_b64 s[38:39], s[46:47], s[64:65]
	s_or_b64 s[48:49], s[48:49], s[38:39]
	s_or_b64 s[42:43], s[44:45], s[46:47]
	s_and_b64 s[44:45], s[44:45], s[46:47]
	s_and_b64 s[44:45], s[44:45], s[40:41]
	s_cmp_eq_u64 s[44:45], 0
	s_cbranch_scc1 .Lna_slow_w1
	ds_read_b128 v[146:149], v199 offset:0
	ds_read_b128 v[150:153], v199 offset:32
	ds_read_b128 v[154:157], v199 offset:64
	ds_read_b128 v[158:161], v199 offset:96
	v_add_u32_e32 v210, s25, v208
	v_exp_f32_e32 v66, v66
	v_exp_f32_e32 v67, v67
	v_exp_f32_e32 v68, v68
	v_exp_f32_e32 v69, v69
	v_add_f32_e32 v213, v213, v66
	v_add_f32_e32 v214, v214, v67
	s_waitcnt lgkmcnt(3)
	v_mfma_f32_32x32x16_bf16 v[34:49], v[146:149], v[98:101], v[114:129]
	ds_read_b64 v[162:163], v201 offset:8704
	ds_read_b64 v[164:165], v201 offset:8720
	v_add_f32_e32 v213, v213, v68
	v_add_f32_e32 v214, v214, v69
	v_exp_f32_e32 v70, v70
	v_exp_f32_e32 v71, v71
	v_exp_f32_e32 v72, v72
	v_exp_f32_e32 v73, v73
	s_waitcnt lgkmcnt(4)
	v_mfma_f32_32x32x16_bf16 v[34:49], v[150:153], v[102:105], v[34:49]
	ds_read_b64 v[166:167], v201 offset:13056
	ds_read_b64 v[168:169], v201 offset:13072
	v_add_f32_e32 v213, v213, v70
	v_add_f32_e32 v214, v214, v71
	v_add_f32_e32 v213, v213, v72
	v_add_f32_e32 v214, v214, v73
	v_cvt_pk_bf16_f32 v66, v66, v67
	v_cvt_pk_bf16_f32 v67, v68, v69
	v_cvt_pk_bf16_f32 v68, v70, v71
	v_cvt_pk_bf16_f32 v69, v72, v73
	s_waitcnt lgkmcnt(5)
	v_mfma_f32_32x32x16_bf16 v[34:49], v[154:157], v[106:109], v[34:49]
	ds_read_b64 v[170:171], v201 offset:8736
	ds_read_b64 v[172:173], v201 offset:8752
	v_exp_f32_e32 v74, v74
	v_exp_f32_e32 v75, v75
	v_exp_f32_e32 v76, v76
	v_exp_f32_e32 v77, v77
	v_add_f32_e32 v213, v213, v74
	s_waitcnt lgkmcnt(6)
	v_mfma_f32_32x32x16_bf16 v[34:49], v[158:161], v[110:113], v[34:49]
	ds_read_b64 v[174:175], v201 offset:13088
	ds_read_b64 v[176:177], v201 offset:13104
	ds_read_b128 v[146:149], v210 offset:0
	ds_read_b128 v[150:153], v210 offset:32
	ds_read_b128 v[154:157], v210 offset:64
	ds_read_b128 v[158:161], v210 offset:96
	v_add_f32_e32 v214, v214, v75
	v_add_f32_e32 v213, v213, v76
	v_add_f32_e32 v214, v214, v77
	v_exp_f32_e32 v78, v78
	v_exp_f32_e32 v79, v79
	v_exp_f32_e32 v80, v80
	s_waitcnt lgkmcnt(10)
	v_mfma_f32_32x32x16_bf16 v[2:17], v[162:165], v[66:69], v[2:17]
	v_exp_f32_e32 v81, v81
	v_add_f32_e32 v213, v213, v78
	v_add_f32_e32 v214, v214, v79
	v_add_f32_e32 v213, v213, v80
	v_add_f32_e32 v214, v214, v81
	v_cvt_pk_bf16_f32 v74, v74, v75
	v_cvt_pk_bf16_f32 v75, v76, v77
	v_cvt_pk_bf16_f32 v76, v78, v79
	s_waitcnt lgkmcnt(8)
	v_mfma_f32_32x32x16_bf16 v[18:33], v[166:169], v[66:69], v[18:33]
	v_cvt_pk_bf16_f32 v77, v80, v81
	s_waitcnt lgkmcnt(0)
	v_add_f32_e32 v34, v34, v146
	v_add_f32_e32 v35, v35, v147
	v_add_f32_e32 v36, v36, v148
	v_add_f32_e32 v37, v37, v149
	v_add_f32_e32 v38, v38, v150
	v_add_f32_e32 v39, v39, v151
	v_add_f32_e32 v40, v40, v152
	v_add_f32_e32 v41, v41, v153
	v_mfma_f32_32x32x16_bf16 v[2:17], v[170:173], v[74:77], v[2:17]
	v_add_f32_e32 v42, v42, v154
	v_add_f32_e32 v43, v43, v155
	v_add_f32_e32 v44, v44, v156
	v_add_f32_e32 v45, v45, v157
	v_add_f32_e32 v46, v46, v158
	v_add_f32_e32 v47, v47, v159
	v_add_f32_e32 v48, v48, v160
	v_add_f32_e32 v49, v49, v161
	v_max3_f32 v216, v34, v35, v36
	v_mfma_f32_32x32x16_bf16 v[18:33], v[174:177], v[74:77], v[18:33]
	s_waitcnt vmcnt(2)
	ds_write_b128 v204, v[230:233] offset:9216
	ds_write_b64 v205, v[234:235] offset:0
	ds_write_b64 v205, v[236:237] offset:8
	global_load_dwordx4 v[230:233], v206, s[12:13]
	s_add_i32 s20, s20, 1
	s_add_u32 s12, s12, 0x2000
	s_addc_u32 s13, s13, 0
	s_cmp_eq_u32 s20, s22
	s_cselect_b32 s12, s16, s12
	s_cselect_b32 s13, s17, s13
	global_load_dwordx4 v[234:237], v207, s[14:15]
	s_add_i32 s21, s21, 1
	s_add_u32 s14, s14, 0x80
	s_addc_u32 s15, s15, 0
	s_cmp_eq_u32 s21, s22
	s_cselect_b32 s14, s18, s14
	s_cselect_b32 s15, s19, s15
	v_max3_f32 v217, v42, v43, v44
	v_max3_f32 v216, v216, v37, v38
	v_max3_f32 v217, v217, v45, v46
	v_max3_f32 v216, v216, v39, v40
	v_max3_f32 v217, v217, v47, v48
	v_max_f32_e32 v216, v216, v41
	v_max_f32_e32 v217, v217, v49
	v_max_f32_e32 v216, v216, v217
	v_cmp_lt_f32_e32 vcc, 4.0, v216
	s_or_b64 s[28:29], vcc, s[26:27]
	s_cmp_lg_u64 s[28:29], 0
	s_cbranch_scc0 .Lna_nr_w1f
	v_mov_b32_e32 v217, v216
	s_nop 1
	v_permlane32_swap_b32_e32 v216, v217
	v_max_f32_e32 v215, v216, v217
	s_nop 15
	v_max_f32_e32 v216, v215, v220
	v_cmp_lt_f32_e32 vcc, 0xf0c9f2ca, v215
	s_nop 1
	v_cndmask_b32_e32 v216, 0, v216, vcc
	v_exp_f32_e64 v217, -v216
	v_add_f32_e32 v212, v212, v216
	v_and_b32_e32 v217, v217, v221
	v_sub_f32_e32 v34, v34, v216
	v_sub_f32_e32 v35, v35, v216
	v_sub_f32_e32 v36, v36, v216
	v_sub_f32_e32 v37, v37, v216
	v_sub_f32_e32 v38, v38, v216
	v_sub_f32_e32 v39, v39, v216
	v_sub_f32_e32 v40, v40, v216
	v_sub_f32_e32 v41, v41, v216
	v_sub_f32_e32 v42, v42, v216
	v_sub_f32_e32 v43, v43, v216
	v_sub_f32_e32 v44, v44, v216
	v_sub_f32_e32 v45, v45, v216
	v_sub_f32_e32 v46, v46, v216
	v_sub_f32_e32 v47, v47, v216
	v_sub_f32_e32 v48, v48, v216
	v_sub_f32_e32 v49, v49, v216
	v_sub_f32_e32 v114, v114, v216
	v_sub_f32_e32 v115, v115, v216
	v_sub_f32_e32 v116, v116, v216
	v_sub_f32_e32 v117, v117, v216
	v_sub_f32_e32 v118, v118, v216
	v_sub_f32_e32 v119, v119, v216
	v_sub_f32_e32 v120, v120, v216
	v_sub_f32_e32 v121, v121, v216
	v_sub_f32_e32 v122, v122, v216
	v_sub_f32_e32 v123, v123, v216
	v_sub_f32_e32 v124, v124, v216
	v_sub_f32_e32 v125, v125, v216
	v_sub_f32_e32 v126, v126, v216
	v_sub_f32_e32 v127, v127, v216
	v_sub_f32_e32 v128, v128, v216
	v_sub_f32_e32 v129, v129, v216
	v_mul_f32_e32 v213, v213, v217
	v_mul_f32_e32 v214, v214, v217
	v_mul_f32_e32 v2, v2, v217
	v_mul_f32_e32 v3, v3, v217
	v_mul_f32_e32 v4, v4, v217
	v_mul_f32_e32 v5, v5, v217
	v_mul_f32_e32 v6, v6, v217
	v_mul_f32_e32 v7, v7, v217
	v_mul_f32_e32 v8, v8, v217
	v_mul_f32_e32 v9, v9, v217
	v_mul_f32_e32 v10, v10, v217
	v_mul_f32_e32 v11, v11, v217
	v_mul_f32_e32 v12, v12, v217
	v_mul_f32_e32 v13, v13, v217
	v_mul_f32_e32 v14, v14, v217
	v_mul_f32_e32 v15, v15, v217
	v_mul_f32_e32 v16, v16, v217
	v_mul_f32_e32 v17, v17, v217
	v_mul_f32_e32 v18, v18, v217
	v_mul_f32_e32 v19, v19, v217
	v_mul_f32_e32 v20, v20, v217
	v_mul_f32_e32 v21, v21, v217
	v_mul_f32_e32 v22, v22, v217
	v_mul_f32_e32 v23, v23, v217
	v_mul_f32_e32 v24, v24, v217
	v_mul_f32_e32 v25, v25, v217
	v_mul_f32_e32 v26, v26, v217
	v_mul_f32_e32 v27, v27, v217
	v_mul_f32_e32 v28, v28, v217
	v_mul_f32_e32 v29, v29, v217
	v_mul_f32_e32 v30, v30, v217
	v_mul_f32_e32 v31, v31, v217
	v_mul_f32_e32 v32, v32, v217
	v_mul_f32_e32 v33, v33, v217
	v_cndmask_b32_e32 v220, v220, v228, vcc
	v_cndmask_b32_e64 v221, v221, -1, vcc
	s_andn2_b64 s[26:27], s[26:27], vcc

.Lna_sl_a_w1s:
	s_waitcnt lgkmcnt(0)
	s_cmp_eq_u64 s[42:43], 0
	s_cbranch_scc1 .Lna_sl_b_w1s
	ds_read_b128 v[146:149], v199 offset:0
	ds_read_b128 v[150:153], v199 offset:32
	ds_read_b128 v[154:157], v199 offset:64
	ds_read_b128 v[158:161], v199 offset:96
	s_waitcnt lgkmcnt(3)
	v_mfma_f32_32x32x16_bf16 v[34:49], v[146:149], v[98:101], v[114:129]
	s_waitcnt lgkmcnt(2)
	v_mfma_f32_32x32x16_bf16 v[34:49], v[150:153], v[102:105], v[34:49]
	s_waitcnt lgkmcnt(1)
	v_mfma_f32_32x32x16_bf16 v[34:49], v[154:157], v[106:109], v[34:49]
	s_waitcnt lgkmcnt(0)
	v_mfma_f32_32x32x16_bf16 v[34:49], v[158:161], v[110:113], v[34:49]
	v_add_u32_e32 v210, s25, v208
	ds_read_b128 v[146:149], v210 offset:0
	ds_read_b128 v[150:153], v210 offset:32
	ds_read_b128 v[154:157], v210 offset:64
	ds_read_b128 v[158:161], v210 offset:96
	s_waitcnt lgkmcnt(0)
	s_nop 15
	v_add_f32_e32 v34, v34, v146
	v_add_f32_e32 v35, v35, v147
	v_add_f32_e32 v36, v36, v148
	v_add_f32_e32 v37, v37, v149
	v_add_f32_e32 v38, v38, v150
	v_add_f32_e32 v39, v39, v151
	v_add_f32_e32 v40, v40, v152
	v_add_f32_e32 v41, v41, v153
	v_add_f32_e32 v42, v42, v154
	v_add_f32_e32 v43, v43, v155
	v_add_f32_e32 v44, v44, v156
	v_add_f32_e32 v45, v45, v157
	v_add_f32_e32 v46, v46, v158
	v_add_f32_e32 v47, v47, v159
	v_add_f32_e32 v48, v48, v160
	v_add_f32_e32 v49, v49, v161
	v_cndmask_b32_e64 v34, v229, v34, s[48:49]
	v_cndmask_b32_e64 v35, v229, v35, s[48:49]
	v_cndmask_b32_e64 v36, v229, v36, s[48:49]
	v_cndmask_b32_e64 v37, v229, v37, s[48:49]
	v_cndmask_b32_e64 v38, v229, v38, s[48:49]
	v_cndmask_b32_e64 v39, v229, v39, s[48:49]
	v_cndmask_b32_e64 v40, v229, v40, s[48:49]
	v_cndmask_b32_e64 v41, v229, v41, s[48:49]
	v_cndmask_b32_e64 v42, v229, v42, s[48:49]
	v_cndmask_b32_e64 v43, v229, v43, s[48:49]
	v_cndmask_b32_e64 v44, v229, v44, s[48:49]
	v_cndmask_b32_e64 v45, v229, v45, s[48:49]
	v_cndmask_b32_e64 v46, v229, v46, s[48:49]
	v_cndmask_b32_e64 v47, v229, v47, s[48:49]
	v_cndmask_b32_e64 v48, v229, v48, s[48:49]
	v_cndmask_b32_e64 v49, v229, v49, s[48:49]
	v_max3_f32 v216, v34, v35, v36
	v_max3_f32 v217, v42, v43, v44
	v_max3_f32 v216, v216, v37, v38
	v_max3_f32 v217, v217, v45, v46
	v_max3_f32 v216, v216, v39, v40
	v_max3_f32 v217, v217, v47, v48
	v_max_f32_e32 v216, v216, v41
	v_max_f32_e32 v217, v217, v49
	v_max_f32_e32 v216, v216, v217
	v_cmp_lt_f32_e32 vcc, 4.0, v216
	s_or_b64 s[28:29], vcc, s[26:27]
	s_cmp_lg_u64 s[28:29], 0
	s_cbranch_scc0 .Lna_nr_w1s
	v_mov_b32_e32 v217, v216
	s_nop 1
	v_permlane32_swap_b32_e32 v216, v217
	v_max_f32_e32 v215, v216, v217
	s_nop 15
	v_max_f32_e32 v216, v215, v220
	v_cmp_lt_f32_e32 vcc, 0xf0c9f2ca, v215
	s_nop 1
	v_cndmask_b32_e32 v216, 0, v216, vcc
	v_exp_f32_e64 v217, -v216
	v_add_f32_e32 v212, v212, v216
	v_and_b32_e32 v217, v217, v221
	v_sub_f32_e32 v34, v34, v216
	v_sub_f32_e32 v35, v35, v216
	v_sub_f32_e32 v36, v36, v216
	v_sub_f32_e32 v37, v37, v216
	v_sub_f32_e32 v38, v38, v216
	v_sub_f32_e32 v39, v39, v216
	v_sub_f32_e32 v40, v40, v216
	v_sub_f32_e32 v41, v41, v216
	v_sub_f32_e32 v42, v42, v216
	v_sub_f32_e32 v43, v43, v216
	v_sub_f32_e32 v44, v44, v216
	v_sub_f32_e32 v45, v45, v216
	v_sub_f32_e32 v46, v46, v216
	v_sub_f32_e32 v47, v47, v216
	v_sub_f32_e32 v48, v48, v216
	v_sub_f32_e32 v49, v49, v216
	v_sub_f32_e32 v114, v114, v216
	v_sub_f32_e32 v115, v115, v216
	v_sub_f32_e32 v116, v116, v216
	v_sub_f32_e32 v117, v117, v216
	v_sub_f32_e32 v118, v118, v216
	v_sub_f32_e32 v119, v119, v216
	v_sub_f32_e32 v120, v120, v216
	v_sub_f32_e32 v121, v121, v216
	v_sub_f32_e32 v122, v122, v216
	v_sub_f32_e32 v123, v123, v216
	v_sub_f32_e32 v124, v124, v216
	v_sub_f32_e32 v125, v125, v216
	v_sub_f32_e32 v126, v126, v216
	v_sub_f32_e32 v127, v127, v216
	v_sub_f32_e32 v128, v128, v216
	v_sub_f32_e32 v129, v129, v216
	v_mul_f32_e32 v213, v213, v217
	v_mul_f32_e32 v214, v214, v217
	v_mul_f32_e32 v2, v2, v217
	v_mul_f32_e32 v3, v3, v217
	v_mul_f32_e32 v4, v4, v217
	v_mul_f32_e32 v5, v5, v217
	v_mul_f32_e32 v6, v6, v217
	v_mul_f32_e32 v7, v7, v217
	v_mul_f32_e32 v8, v8, v217
	v_mul_f32_e32 v9, v9, v217
	v_mul_f32_e32 v10, v10, v217
	v_mul_f32_e32 v11, v11, v217
	v_mul_f32_e32 v12, v12, v217
	v_mul_f32_e32 v13, v13, v217
	v_mul_f32_e32 v14, v14, v217
	v_mul_f32_e32 v15, v15, v217
	v_mul_f32_e32 v16, v16, v217
	v_mul_f32_e32 v17, v17, v217
	v_mul_f32_e32 v18, v18, v217
	v_mul_f32_e32 v19, v19, v217
	v_mul_f32_e32 v20, v20, v217
	v_mul_f32_e32 v21, v21, v217
	v_mul_f32_e32 v22, v22, v217
	v_mul_f32_e32 v23, v23, v217
	v_mul_f32_e32 v24, v24, v217
	v_mul_f32_e32 v25, v25, v217
	v_mul_f32_e32 v26, v26, v217
	v_mul_f32_e32 v27, v27, v217
	v_mul_f32_e32 v28, v28, v217
	v_mul_f32_e32 v29, v29, v217
	v_mul_f32_e32 v30, v30, v217
	v_mul_f32_e32 v31, v31, v217
	v_mul_f32_e32 v32, v32, v217
	v_mul_f32_e32 v33, v33, v217
	v_cndmask_b32_e32 v220, v220, v228, vcc
	v_cndmask_b32_e64 v221, v221, -1, vcc
	s_andn2_b64 s[26:27], s[26:27], vcc

.Lna_done_w1:
	s_add_i32 s24, s24, 1
	s_add_i32 s25, s25, 0x150
	s_sub_i32 s36, s24, s23
	s_cmp_lt_u32 s36, s63
	s_cselect_b64 s[40:41], -1, 0
	s_add_i32 s36, s36, 1
	s_cmp_lt_u32 s36, 8
	s_cselect_b64 s[44:45], -1, 0
	s_sub_i32 s37, s36, s62
	s_cmp_lt_u32 s37, 8
	s_cselect_b64 s[46:47], -1, 0
	s_and_b64 s[48:49], s[44:45], s[64:65]
	s_andn2_b64 s[38:39], s[46:47], s[64:65]
	s_or_b64 s[48:49], s[48:49], s[38:39]
	s_or_b64 s[42:43], s[44:45], s[46:47]
	s_and_b64 s[44:45], s[44:45], s[46:47]
	s_and_b64 s[44:45], s[44:45], s[40:41]
	s_cmp_eq_u64 s[44:45], 0
	s_cbranch_scc1 .Lna_slow_w0
	ds_read_b128 v[146:149], v199 offset:9216
	ds_read_b128 v[150:153], v199 offset:9248
	ds_read_b128 v[154:157], v199 offset:9280
	ds_read_b128 v[158:161], v199 offset:9312
	v_add_u32_e32 v210, s25, v208
	v_exp_f32_e32 v34, v34
	v_exp_f32_e32 v35, v35
	v_exp_f32_e32 v36, v36
	v_exp_f32_e32 v37, v37
	v_add_f32_e32 v213, v213, v34
	v_add_f32_e32 v214, v214, v35
	s_waitcnt lgkmcnt(3)
	v_mfma_f32_32x32x16_bf16 v[66:81], v[146:149], v[98:101], v[114:129]
	ds_read_b64 v[162:163], v201 offset:0
	ds_read_b64 v[164:165], v201 offset:16
	v_add_f32_e32 v213, v213, v36
	v_add_f32_e32 v214, v214, v37
	v_exp_f32_e32 v38, v38
	v_exp_f32_e32 v39, v39
	v_exp_f32_e32 v40, v40
	v_exp_f32_e32 v41, v41
	s_waitcnt lgkmcnt(4)
	v_mfma_f32_32x32x16_bf16 v[66:81], v[150:153], v[102:105], v[66:81]
	ds_read_b64 v[166:167], v201 offset:4352
	ds_read_b64 v[168:169], v201 offset:4368
	v_add_f32_e32 v213, v213, v38
	v_add_f32_e32 v214, v214, v39
	v_add_f32_e32 v213, v213, v40
	v_add_f32_e32 v214, v214, v41
	v_cvt_pk_bf16_f32 v34, v34, v35
	v_cvt_pk_bf16_f32 v35, v36, v37
	v_cvt_pk_bf16_f32 v36, v38, v39
	v_cvt_pk_bf16_f32 v37, v40, v41
	s_waitcnt lgkmcnt(5)
	v_mfma_f32_32x32x16_bf16 v[66:81], v[154:157], v[106:109], v[66:81]
	ds_read_b64 v[170:171], v201 offset:32
	ds_read_b64 v[172:173], v201 offset:48
	v_exp_f32_e32 v42, v42
	v_exp_f32_e32 v43, v43
	v_exp_f32_e32 v44, v44
	v_exp_f32_e32 v45, v45
	v_add_f32_e32 v213, v213, v42
	s_waitcnt lgkmcnt(6)
	v_mfma_f32_32x32x16_bf16 v[66:81], v[158:161], v[110:113], v[66:81]
	ds_read_b64 v[174:175], v201 offset:4384
	ds_read_b64 v[176:177], v201 offset:4400
	ds_read_b128 v[146:149], v210 offset:0
	ds_read_b128 v[150:153], v210 offset:32
	ds_read_b128 v[154:157], v210 offset:64
	ds_read_b128 v[158:161], v210 offset:96
	v_add_f32_e32 v214, v214, v43
	v_add_f32_e32 v213, v213, v44
	v_add_f32_e32 v214, v214, v45
	v_exp_f32_e32 v46, v46
	v_exp_f32_e32 v47, v47
	v_exp_f32_e32 v48, v48
	s_waitcnt lgkmcnt(10)
	v_mfma_f32_32x32x16_bf16 v[2:17], v[162:165], v[34:37], v[2:17]
	v_exp_f32_e32 v49, v49
	v_add_f32_e32 v213, v213, v46
	v_add_f32_e32 v214, v214, v47
	v_add_f32_e32 v213, v213, v48
	v_add_f32_e32 v214, v214, v49
	v_cvt_pk_bf16_f32 v42, v42, v43
	v_cvt_pk_bf16_f32 v43, v44, v45
	v_cvt_pk_bf16_f32 v44, v46, v47
	s_waitcnt lgkmcnt(8)
	v_mfma_f32_32x32x16_bf16 v[18:33], v[166:169], v[34:37], v[18:33]
	v_cvt_pk_bf16_f32 v45, v48, v49
	s_waitcnt lgkmcnt(0)
	v_add_f32_e32 v66, v66, v146
	v_add_f32_e32 v67, v67, v147
	v_add_f32_e32 v68, v68, v148
	v_add_f32_e32 v69, v69, v149
	v_add_f32_e32 v70, v70, v150
	v_add_f32_e32 v71, v71, v151
	v_add_f32_e32 v72, v72, v152
	v_add_f32_e32 v73, v73, v153
	v_mfma_f32_32x32x16_bf16 v[2:17], v[170:173], v[42:45], v[2:17]
	v_add_f32_e32 v74, v74, v154
	v_add_f32_e32 v75, v75, v155
	v_add_f32_e32 v76, v76, v156
	v_add_f32_e32 v77, v77, v157
	v_add_f32_e32 v78, v78, v158
	v_add_f32_e32 v79, v79, v159
	v_add_f32_e32 v80, v80, v160
	v_add_f32_e32 v81, v81, v161
	v_max3_f32 v216, v66, v67, v68
	v_mfma_f32_32x32x16_bf16 v[18:33], v[174:177], v[42:45], v[18:33]
	s_waitcnt vmcnt(2)
	ds_write_b128 v204, v[188:191] offset:0
	ds_write_b64 v205, v[192:193] offset:8704
	ds_write_b64 v205, v[194:195] offset:8712
	global_load_dwordx4 v[188:191], v206, s[12:13]
	s_add_i32 s20, s20, 1
	s_add_u32 s12, s12, 0x2000
	s_addc_u32 s13, s13, 0
	s_cmp_eq_u32 s20, s22
	s_cselect_b32 s12, s16, s12
	s_cselect_b32 s13, s17, s13
	global_load_dwordx4 v[192:195], v207, s[14:15]
	s_add_i32 s21, s21, 1
	s_add_u32 s14, s14, 0x80
	s_addc_u32 s15, s15, 0
	s_cmp_eq_u32 s21, s22
	s_cselect_b32 s14, s18, s14
	s_cselect_b32 s15, s19, s15
	v_max3_f32 v217, v74, v75, v76
	v_max3_f32 v216, v216, v69, v70
	v_max3_f32 v217, v217, v77, v78
	v_max3_f32 v216, v216, v71, v72
	v_max3_f32 v217, v217, v79, v80
	v_max_f32_e32 v216, v216, v73
	v_max_f32_e32 v217, v217, v81
	v_max_f32_e32 v216, v216, v217
	v_cmp_lt_f32_e32 vcc, 4.0, v216
	s_or_b64 s[28:29], vcc, s[26:27]
	s_cmp_lg_u64 s[28:29], 0
	s_cbranch_scc0 .Lna_nr_w0f
	v_mov_b32_e32 v217, v216
	s_nop 1
	v_permlane32_swap_b32_e32 v216, v217
	v_max_f32_e32 v215, v216, v217
	s_nop 15
	v_max_f32_e32 v216, v215, v220
	v_cmp_lt_f32_e32 vcc, 0xf0c9f2ca, v215
	s_nop 1
	v_cndmask_b32_e32 v216, 0, v216, vcc
	v_exp_f32_e64 v217, -v216
	v_add_f32_e32 v212, v212, v216
	v_and_b32_e32 v217, v217, v221
	v_sub_f32_e32 v66, v66, v216
	v_sub_f32_e32 v67, v67, v216
	v_sub_f32_e32 v68, v68, v216
	v_sub_f32_e32 v69, v69, v216
	v_sub_f32_e32 v70, v70, v216
	v_sub_f32_e32 v71, v71, v216
	v_sub_f32_e32 v72, v72, v216
	v_sub_f32_e32 v73, v73, v216
	v_sub_f32_e32 v74, v74, v216
	v_sub_f32_e32 v75, v75, v216
	v_sub_f32_e32 v76, v76, v216
	v_sub_f32_e32 v77, v77, v216
	v_sub_f32_e32 v78, v78, v216
	v_sub_f32_e32 v79, v79, v216
	v_sub_f32_e32 v80, v80, v216
	v_sub_f32_e32 v81, v81, v216
	v_sub_f32_e32 v114, v114, v216
	v_sub_f32_e32 v115, v115, v216
	v_sub_f32_e32 v116, v116, v216
	v_sub_f32_e32 v117, v117, v216
	v_sub_f32_e32 v118, v118, v216
	v_sub_f32_e32 v119, v119, v216
	v_sub_f32_e32 v120, v120, v216
	v_sub_f32_e32 v121, v121, v216
	v_sub_f32_e32 v122, v122, v216
	v_sub_f32_e32 v123, v123, v216
	v_sub_f32_e32 v124, v124, v216
	v_sub_f32_e32 v125, v125, v216
	v_sub_f32_e32 v126, v126, v216
	v_sub_f32_e32 v127, v127, v216
	v_sub_f32_e32 v128, v128, v216
	v_sub_f32_e32 v129, v129, v216
	v_mul_f32_e32 v213, v213, v217
	v_mul_f32_e32 v214, v214, v217
	v_mul_f32_e32 v2, v2, v217
	v_mul_f32_e32 v3, v3, v217
	v_mul_f32_e32 v4, v4, v217
	v_mul_f32_e32 v5, v5, v217
	v_mul_f32_e32 v6, v6, v217
	v_mul_f32_e32 v7, v7, v217
	v_mul_f32_e32 v8, v8, v217
	v_mul_f32_e32 v9, v9, v217
	v_mul_f32_e32 v10, v10, v217
	v_mul_f32_e32 v11, v11, v217
	v_mul_f32_e32 v12, v12, v217
	v_mul_f32_e32 v13, v13, v217
	v_mul_f32_e32 v14, v14, v217
	v_mul_f32_e32 v15, v15, v217
	v_mul_f32_e32 v16, v16, v217
	v_mul_f32_e32 v17, v17, v217
	v_mul_f32_e32 v18, v18, v217
	v_mul_f32_e32 v19, v19, v217
	v_mul_f32_e32 v20, v20, v217
	v_mul_f32_e32 v21, v21, v217
	v_mul_f32_e32 v22, v22, v217
	v_mul_f32_e32 v23, v23, v217
	v_mul_f32_e32 v24, v24, v217
	v_mul_f32_e32 v25, v25, v217
	v_mul_f32_e32 v26, v26, v217
	v_mul_f32_e32 v27, v27, v217
	v_mul_f32_e32 v28, v28, v217
	v_mul_f32_e32 v29, v29, v217
	v_mul_f32_e32 v30, v30, v217
	v_mul_f32_e32 v31, v31, v217
	v_mul_f32_e32 v32, v32, v217
	v_mul_f32_e32 v33, v33, v217
	v_cndmask_b32_e32 v220, v220, v228, vcc
	v_cndmask_b32_e64 v221, v221, -1, vcc
	s_andn2_b64 s[26:27], s[26:27], vcc

.Lna_sl_a_w0s:
	s_waitcnt lgkmcnt(0)
	s_cmp_eq_u64 s[42:43], 0
	s_cbranch_scc1 .Lna_sl_b_w0s
	ds_read_b128 v[146:149], v199 offset:9216
	ds_read_b128 v[150:153], v199 offset:9248
	ds_read_b128 v[154:157], v199 offset:9280
	ds_read_b128 v[158:161], v199 offset:9312
	s_waitcnt lgkmcnt(3)
	v_mfma_f32_32x32x16_bf16 v[66:81], v[146:149], v[98:101], v[114:129]
	s_waitcnt lgkmcnt(2)
	v_mfma_f32_32x32x16_bf16 v[66:81], v[150:153], v[102:105], v[66:81]
	s_waitcnt lgkmcnt(1)
	v_mfma_f32_32x32x16_bf16 v[66:81], v[154:157], v[106:109], v[66:81]
	s_waitcnt lgkmcnt(0)
	v_mfma_f32_32x32x16_bf16 v[66:81], v[158:161], v[110:113], v[66:81]
	v_add_u32_e32 v210, s25, v208
	ds_read_b128 v[146:149], v210 offset:0
	ds_read_b128 v[150:153], v210 offset:32
	ds_read_b128 v[154:157], v210 offset:64
	ds_read_b128 v[158:161], v210 offset:96
	s_waitcnt lgkmcnt(0)
	s_nop 15
	v_add_f32_e32 v66, v66, v146
	v_add_f32_e32 v67, v67, v147
	v_add_f32_e32 v68, v68, v148
	v_add_f32_e32 v69, v69, v149
	v_add_f32_e32 v70, v70, v150
	v_add_f32_e32 v71, v71, v151
	v_add_f32_e32 v72, v72, v152
	v_add_f32_e32 v73, v73, v153
	v_add_f32_e32 v74, v74, v154
	v_add_f32_e32 v75, v75, v155
	v_add_f32_e32 v76, v76, v156
	v_add_f32_e32 v77, v77, v157
	v_add_f32_e32 v78, v78, v158
	v_add_f32_e32 v79, v79, v159
	v_add_f32_e32 v80, v80, v160
	v_add_f32_e32 v81, v81, v161
	v_cndmask_b32_e64 v66, v229, v66, s[48:49]
	v_cndmask_b32_e64 v67, v229, v67, s[48:49]
	v_cndmask_b32_e64 v68, v229, v68, s[48:49]
	v_cndmask_b32_e64 v69, v229, v69, s[48:49]
	v_cndmask_b32_e64 v70, v229, v70, s[48:49]
	v_cndmask_b32_e64 v71, v229, v71, s[48:49]
	v_cndmask_b32_e64 v72, v229, v72, s[48:49]
	v_cndmask_b32_e64 v73, v229, v73, s[48:49]
	v_cndmask_b32_e64 v74, v229, v74, s[48:49]
	v_cndmask_b32_e64 v75, v229, v75, s[48:49]
	v_cndmask_b32_e64 v76, v229, v76, s[48:49]
	v_cndmask_b32_e64 v77, v229, v77, s[48:49]
	v_cndmask_b32_e64 v78, v229, v78, s[48:49]
	v_cndmask_b32_e64 v79, v229, v79, s[48:49]
	v_cndmask_b32_e64 v80, v229, v80, s[48:49]
	v_cndmask_b32_e64 v81, v229, v81, s[48:49]
	v_max3_f32 v216, v66, v67, v68
	v_max3_f32 v217, v74, v75, v76
	v_max3_f32 v216, v216, v69, v70
	v_max3_f32 v217, v217, v77, v78
	v_max3_f32 v216, v216, v71, v72
	v_max3_f32 v217, v217, v79, v80
	v_max_f32_e32 v216, v216, v73
	v_max_f32_e32 v217, v217, v81
	v_max_f32_e32 v216, v216, v217
	v_cmp_lt_f32_e32 vcc, 4.0, v216
	s_or_b64 s[28:29], vcc, s[26:27]
	s_cmp_lg_u64 s[28:29], 0
	s_cbranch_scc0 .Lna_nr_w0s
	v_mov_b32_e32 v217, v216
	s_nop 1
	v_permlane32_swap_b32_e32 v216, v217
	v_max_f32_e32 v215, v216, v217
	s_nop 15
	v_max_f32_e32 v216, v215, v220
	v_cmp_lt_f32_e32 vcc, 0xf0c9f2ca, v215
	s_nop 1
	v_cndmask_b32_e32 v216, 0, v216, vcc
	v_exp_f32_e64 v217, -v216
	v_add_f32_e32 v212, v212, v216
	v_and_b32_e32 v217, v217, v221
	v_sub_f32_e32 v66, v66, v216
	v_sub_f32_e32 v67, v67, v216
	v_sub_f32_e32 v68, v68, v216
	v_sub_f32_e32 v69, v69, v216
	v_sub_f32_e32 v70, v70, v216
	v_sub_f32_e32 v71, v71, v216
	v_sub_f32_e32 v72, v72, v216
	v_sub_f32_e32 v73, v73, v216
	v_sub_f32_e32 v74, v74, v216
	v_sub_f32_e32 v75, v75, v216
	v_sub_f32_e32 v76, v76, v216
	v_sub_f32_e32 v77, v77, v216
	v_sub_f32_e32 v78, v78, v216
	v_sub_f32_e32 v79, v79, v216
	v_sub_f32_e32 v80, v80, v216
	v_sub_f32_e32 v81, v81, v216
	v_sub_f32_e32 v114, v114, v216
	v_sub_f32_e32 v115, v115, v216
	v_sub_f32_e32 v116, v116, v216
	v_sub_f32_e32 v117, v117, v216
	v_sub_f32_e32 v118, v118, v216
	v_sub_f32_e32 v119, v119, v216
	v_sub_f32_e32 v120, v120, v216
	v_sub_f32_e32 v121, v121, v216
	v_sub_f32_e32 v122, v122, v216
	v_sub_f32_e32 v123, v123, v216
	v_sub_f32_e32 v124, v124, v216
	v_sub_f32_e32 v125, v125, v216
	v_sub_f32_e32 v126, v126, v216
	v_sub_f32_e32 v127, v127, v216
	v_sub_f32_e32 v128, v128, v216
	v_sub_f32_e32 v129, v129, v216
	v_mul_f32_e32 v213, v213, v217
	v_mul_f32_e32 v214, v214, v217
	v_mul_f32_e32 v2, v2, v217
	v_mul_f32_e32 v3, v3, v217
	v_mul_f32_e32 v4, v4, v217
	v_mul_f32_e32 v5, v5, v217
	v_mul_f32_e32 v6, v6, v217
	v_mul_f32_e32 v7, v7, v217
	v_mul_f32_e32 v8, v8, v217
	v_mul_f32_e32 v9, v9, v217
	v_mul_f32_e32 v10, v10, v217
	v_mul_f32_e32 v11, v11, v217
	v_mul_f32_e32 v12, v12, v217
	v_mul_f32_e32 v13, v13, v217
	v_mul_f32_e32 v14, v14, v217
	v_mul_f32_e32 v15, v15, v217
	v_mul_f32_e32 v16, v16, v217
	v_mul_f32_e32 v17, v17, v217
	v_mul_f32_e32 v18, v18, v217
	v_mul_f32_e32 v19, v19, v217
	v_mul_f32_e32 v20, v20, v217
	v_mul_f32_e32 v21, v21, v217
	v_mul_f32_e32 v22, v22, v217
	v_mul_f32_e32 v23, v23, v217
	v_mul_f32_e32 v24, v24, v217
	v_mul_f32_e32 v25, v25, v217
	v_mul_f32_e32 v26, v26, v217
	v_mul_f32_e32 v27, v27, v217
	v_mul_f32_e32 v28, v28, v217
	v_mul_f32_e32 v29, v29, v217
	v_mul_f32_e32 v30, v30, v217
	v_mul_f32_e32 v31, v31, v217
	v_mul_f32_e32 v32, v32, v217
	v_mul_f32_e32 v33, v33, v217
	v_cndmask_b32_e32 v220, v220, v228, vcc
	v_cndmask_b32_e64 v221, v221, -1, vcc
	s_andn2_b64 s[26:27], s[26:27], vcc

.Lna_done_w0:
	s_add_i32 s24, s24, 1
	s_add_i32 s25, s25, 0x150
	s_add_i32 s33, s33, -1
	s_cmp_lg_u32 s33, 0
	s_cbranch_scc1 .Lna_wloop
	v_sub_f32_e32 v114, 0, v212
	v_mov_b32_e32 v115, v114
	v_mov_b32_e32 v116, v114
	v_mov_b32_e32 v117, v114
	v_mov_b32_e32 v118, v114
	v_mov_b32_e32 v119, v114
	v_mov_b32_e32 v120, v114
	v_mov_b32_e32 v121, v114
	v_mov_b32_e32 v122, v114
	v_mov_b32_e32 v123, v114
	v_mov_b32_e32 v124, v114
	v_mov_b32_e32 v125, v114
	v_mov_b32_e32 v126, v114
	v_mov_b32_e32 v127, v114
	v_mov_b32_e32 v128, v114
	v_mov_b32_e32 v129, v114
	v_mov_b32_e32 v130, v114
	v_mov_b32_e32 v131, v114
	v_mov_b32_e32 v132, v114
	v_mov_b32_e32 v133, v114
	v_mov_b32_e32 v134, v114
	v_mov_b32_e32 v135, v114
	v_mov_b32_e32 v136, v114
	v_mov_b32_e32 v137, v114
	v_mov_b32_e32 v138, v114
	v_mov_b32_e32 v139, v114
	v_mov_b32_e32 v140, v114
	v_mov_b32_e32 v141, v114
	v_mov_b32_e32 v142, v114
	v_mov_b32_e32 v143, v114
	v_mov_b32_e32 v144, v114
	v_mov_b32_e32 v145, v114
	s_sub_i32 s36, s24, s23
	s_cmp_lt_u32 s36, s63
	s_cselect_b64 s[40:41], -1, 0
	s_mov_b64 s[42:43], -1
	s_cmp_eq_u64 s[40:41], 0
	s_cbranch_scc1 .Lna_slow_wc
	ds_read_b128 v[146:149], v200 offset:0
	ds_read_b128 v[150:153], v200 offset:4608
	ds_read_b128 v[154:157], v200 offset:32
	ds_read_b128 v[158:161], v200 offset:4640
	v_exp_f32_e32 v66, v66
	v_exp_f32_e32 v67, v67
	v_exp_f32_e32 v68, v68
	s_waitcnt lgkmcnt(2)
	v_mfma_f32_32x32x16_bf16 v[34:49], v[146:149], v[98:101], v[114:129]
	ds_read_b128 v[146:149], v200 offset:64
	v_exp_f32_e32 v69, v69
	v_add_f32_e32 v213, v213, v66
	v_add_f32_e32 v214, v214, v67
	v_add_f32_e32 v213, v213, v68
	v_add_f32_e32 v214, v214, v69
	v_mfma_f32_32x32x16_bf16 v[50:65], v[150:153], v[98:101], v[130:145]
	ds_read_b128 v[150:153], v200 offset:4672
	v_exp_f32_e32 v70, v70
	v_exp_f32_e32 v71, v71
	v_exp_f32_e32 v72, v72
	s_waitcnt lgkmcnt(2)
	v_mfma_f32_32x32x16_bf16 v[34:49], v[154:157], v[102:105], v[34:49]
	ds_read_b128 v[154:157], v200 offset:96
	v_exp_f32_e32 v73, v73
	v_add_f32_e32 v213, v213, v70
	v_add_f32_e32 v214, v214, v71
	v_add_f32_e32 v213, v213, v72
	v_mfma_f32_32x32x16_bf16 v[50:65], v[158:161], v[102:105], v[50:65]
	ds_read_b128 v[158:161], v200 offset:4704
	v_add_f32_e32 v214, v214, v73
	v_cvt_pk_bf16_f32 v66, v66, v67
	v_cvt_pk_bf16_f32 v67, v68, v69
	v_cvt_pk_bf16_f32 v68, v70, v71
	v_cvt_pk_bf16_f32 v69, v72, v73
	v_exp_f32_e32 v74, v74
	s_waitcnt lgkmcnt(2)
	v_mfma_f32_32x32x16_bf16 v[34:49], v[146:149], v[106:109], v[34:49]
	ds_read_b64 v[162:163], v201 offset:8704
	ds_read_b64 v[164:165], v201 offset:8720
	v_exp_f32_e32 v75, v75
	v_exp_f32_e32 v76, v76
	v_exp_f32_e32 v77, v77
	v_mfma_f32_32x32x16_bf16 v[50:65], v[150:153], v[106:109], v[50:65]
	ds_read_b64 v[166:167], v201 offset:13056
	ds_read_b64 v[168:169], v201 offset:13072
	v_add_f32_e32 v213, v213, v74
	v_add_f32_e32 v214, v214, v75
	v_add_f32_e32 v213, v213, v76
	v_add_f32_e32 v214, v214, v77
	s_waitcnt lgkmcnt(4)
	v_mfma_f32_32x32x16_bf16 v[34:49], v[154:157], v[110:113], v[34:49]
	ds_read_b64 v[170:171], v201 offset:8736
	ds_read_b64 v[172:173], v201 offset:8752
	v_exp_f32_e32 v78, v78
	v_exp_f32_e32 v79, v79
	v_exp_f32_e32 v80, v80
	v_mfma_f32_32x32x16_bf16 v[50:65], v[158:161], v[110:113], v[50:65]
	ds_read_b64 v[174:175], v201 offset:13088
	ds_read_b64 v[176:177], v201 offset:13104
	v_exp_f32_e32 v81, v81
	v_add_f32_e32 v213, v213, v78
	v_add_f32_e32 v214, v214, v79
	v_add_f32_e32 v213, v213, v80
	v_add_f32_e32 v214, v214, v81
	s_waitcnt lgkmcnt(6)
	v_mfma_f32_32x32x16_bf16 v[2:17], v[162:165], v[66:69], v[2:17]
	v_cvt_pk_bf16_f32 v74, v74, v75
	v_cvt_pk_bf16_f32 v75, v76, v77
	v_cvt_pk_bf16_f32 v76, v78, v79
	v_cvt_pk_bf16_f32 v77, v80, v81
	s_waitcnt lgkmcnt(4)
	v_mfma_f32_32x32x16_bf16 v[18:33], v[166:169], v[66:69], v[18:33]
	v_max3_f32 v216, v34, v35, v36
	v_max3_f32 v217, v50, v51, v52
	v_max3_f32 v216, v216, v37, v38
	v_max3_f32 v217, v217, v53, v54
	v_max3_f32 v216, v216, v39, v40
	v_max3_f32 v217, v217, v55, v56
	v_max3_f32 v216, v216, v41, v42
	s_waitcnt lgkmcnt(2)
	v_mfma_f32_32x32x16_bf16 v[2:17], v[170:173], v[74:77], v[2:17]
	v_max3_f32 v217, v217, v57, v58
	v_max3_f32 v216, v216, v43, v44
	v_max3_f32 v217, v217, v59, v60
	v_max3_f32 v216, v216, v45, v46
	v_max3_f32 v217, v217, v61, v62
	v_max3_f32 v216, v216, v47, v48
	s_waitcnt lgkmcnt(0)
	v_mfma_f32_32x32x16_bf16 v[18:33], v[174:177], v[74:77], v[18:33]
	s_waitcnt vmcnt(2)
	ds_write_b128 v204, v[230:233] offset:9216
	ds_write_b64 v205, v[234:235] offset:0
	ds_write_b64 v205, v[236:237] offset:8
	global_load_dwordx4 v[230:233], v206, s[12:13]
	s_add_u32 s12, s12, 0x2000
	s_addc_u32 s13, s13, 0
	global_load_dwordx4 v[234:237], v207, s[14:15]
	s_add_u32 s14, s14, 0x80
	s_addc_u32 s15, s15, 0
	v_max3_f32 v217, v217, v63, v64
	v_max_f32_e32 v216, v216, v49
	v_max_f32_e32 v217, v217, v65
	v_max_f32_e32 v216, v216, v217
	v_cmp_lt_f32_e32 vcc, 4.0, v216
	s_cbranch_vccz .Lna_nr_wcf
	v_mov_b32_e32 v217, v216
	s_nop 1
	v_permlane32_swap_b32_e32 v216, v217
	v_max_f32_e32 v215, v216, v217
	s_nop 15
	v_max_f32_e32 v216, v215, v220
	v_exp_f32_e64 v217, -v216
	v_add_f32_e32 v212, v212, v216
	v_and_b32_e32 v217, v217, v221
	v_sub_f32_e32 v34, v34, v216
	v_sub_f32_e32 v35, v35, v216
	v_sub_f32_e32 v36, v36, v216
	v_sub_f32_e32 v37, v37, v216
	v_sub_f32_e32 v38, v38, v216
	v_sub_f32_e32 v39, v39, v216
	v_sub_f32_e32 v40, v40, v216
	v_sub_f32_e32 v41, v41, v216
	v_sub_f32_e32 v42, v42, v216
	v_sub_f32_e32 v43, v43, v216
	v_sub_f32_e32 v44, v44, v216
	v_sub_f32_e32 v45, v45, v216
	v_sub_f32_e32 v46, v46, v216
	v_sub_f32_e32 v47, v47, v216
	v_sub_f32_e32 v48, v48, v216
	v_sub_f32_e32 v49, v49, v216
	v_sub_f32_e32 v50, v50, v216
	v_sub_f32_e32 v51, v51, v216
	v_sub_f32_e32 v52, v52, v216
	v_sub_f32_e32 v53, v53, v216
	v_sub_f32_e32 v54, v54, v216
	v_sub_f32_e32 v55, v55, v216
	v_sub_f32_e32 v56, v56, v216
	v_sub_f32_e32 v57, v57, v216
	v_sub_f32_e32 v58, v58, v216
	v_sub_f32_e32 v59, v59, v216
	v_sub_f32_e32 v60, v60, v216
	v_sub_f32_e32 v61, v61, v216
	v_sub_f32_e32 v62, v62, v216
	v_sub_f32_e32 v63, v63, v216
	v_sub_f32_e32 v64, v64, v216
	v_sub_f32_e32 v65, v65, v216
	v_sub_f32_e32 v114, v114, v216
	v_sub_f32_e32 v115, v115, v216
	v_sub_f32_e32 v116, v116, v216
	v_sub_f32_e32 v117, v117, v216
	v_sub_f32_e32 v118, v118, v216
	v_sub_f32_e32 v119, v119, v216
	v_sub_f32_e32 v120, v120, v216
	v_sub_f32_e32 v121, v121, v216
	v_sub_f32_e32 v122, v122, v216
	v_sub_f32_e32 v123, v123, v216
	v_sub_f32_e32 v124, v124, v216
	v_sub_f32_e32 v125, v125, v216
	v_sub_f32_e32 v126, v126, v216
	v_sub_f32_e32 v127, v127, v216
	v_sub_f32_e32 v128, v128, v216
	v_sub_f32_e32 v129, v129, v216
	v_sub_f32_e32 v130, v130, v216
	v_sub_f32_e32 v131, v131, v216
	v_sub_f32_e32 v132, v132, v216
	v_sub_f32_e32 v133, v133, v216
	v_sub_f32_e32 v134, v134, v216
	v_sub_f32_e32 v135, v135, v216
	v_sub_f32_e32 v136, v136, v216
	v_sub_f32_e32 v137, v137, v216
	v_sub_f32_e32 v138, v138, v216
	v_sub_f32_e32 v139, v139, v216
	v_sub_f32_e32 v140, v140, v216
	v_sub_f32_e32 v141, v141, v216
	v_sub_f32_e32 v142, v142, v216
	v_sub_f32_e32 v143, v143, v216
	v_sub_f32_e32 v144, v144, v216
	v_sub_f32_e32 v145, v145, v216
	v_mul_f32_e32 v213, v213, v217
	v_mul_f32_e32 v214, v214, v217
	v_mul_f32_e32 v2, v2, v217
	v_mul_f32_e32 v3, v3, v217
	v_mul_f32_e32 v4, v4, v217
	v_mul_f32_e32 v5, v5, v217
	v_mul_f32_e32 v6, v6, v217
	v_mul_f32_e32 v7, v7, v217
	v_mul_f32_e32 v8, v8, v217
	v_mul_f32_e32 v9, v9, v217
	v_mul_f32_e32 v10, v10, v217
	v_mul_f32_e32 v11, v11, v217
	v_mul_f32_e32 v12, v12, v217
	v_mul_f32_e32 v13, v13, v217
	v_mul_f32_e32 v14, v14, v217
	v_mul_f32_e32 v15, v15, v217
	v_mul_f32_e32 v16, v16, v217
	v_mul_f32_e32 v17, v17, v217
	v_mul_f32_e32 v18, v18, v217
	v_mul_f32_e32 v19, v19, v217
	v_mul_f32_e32 v20, v20, v217
	v_mul_f32_e32 v21, v21, v217
	v_mul_f32_e32 v22, v22, v217
	v_mul_f32_e32 v23, v23, v217
	v_mul_f32_e32 v24, v24, v217
	v_mul_f32_e32 v25, v25, v217
	v_mul_f32_e32 v26, v26, v217
	v_mul_f32_e32 v27, v27, v217
	v_mul_f32_e32 v28, v28, v217
	v_mul_f32_e32 v29, v29, v217
	v_mul_f32_e32 v30, v30, v217
	v_mul_f32_e32 v31, v31, v217
	v_mul_f32_e32 v32, v32, v217
	v_mul_f32_e32 v33, v33, v217

.Lna_sl_a_wcs:
	s_waitcnt lgkmcnt(0)
	s_cmp_eq_u64 s[42:43], 0
	s_cbranch_scc1 .Lna_sl_b_wcs
	ds_read_b128 v[146:149], v200 offset:0
	ds_read_b128 v[150:153], v200 offset:4608
	ds_read_b128 v[154:157], v200 offset:32
	ds_read_b128 v[158:161], v200 offset:4640
	ds_read_b128 v[162:165], v200 offset:64
	ds_read_b128 v[166:169], v200 offset:4672
	ds_read_b128 v[170:173], v200 offset:96
	ds_read_b128 v[174:177], v200 offset:4704
	s_waitcnt lgkmcnt(7)
	v_mfma_f32_32x32x16_bf16 v[34:49], v[146:149], v[98:101], v[114:129]
	s_waitcnt lgkmcnt(6)
	v_mfma_f32_32x32x16_bf16 v[50:65], v[150:153], v[98:101], v[130:145]
	s_waitcnt lgkmcnt(5)
	v_mfma_f32_32x32x16_bf16 v[34:49], v[154:157], v[102:105], v[34:49]
	s_waitcnt lgkmcnt(4)
	v_mfma_f32_32x32x16_bf16 v[50:65], v[158:161], v[102:105], v[50:65]
	s_waitcnt lgkmcnt(3)
	v_mfma_f32_32x32x16_bf16 v[34:49], v[162:165], v[106:109], v[34:49]
	s_waitcnt lgkmcnt(2)
	v_mfma_f32_32x32x16_bf16 v[50:65], v[166:169], v[106:109], v[50:65]
	s_waitcnt lgkmcnt(1)
	v_mfma_f32_32x32x16_bf16 v[34:49], v[170:173], v[110:113], v[34:49]
	s_waitcnt lgkmcnt(0)
	v_mfma_f32_32x32x16_bf16 v[50:65], v[174:177], v[110:113], v[50:65]
	s_nop 15
	v_max3_f32 v216, v34, v35, v36
	v_max3_f32 v217, v50, v51, v52
	v_max3_f32 v216, v216, v37, v38
	v_max3_f32 v217, v217, v53, v54
	v_max3_f32 v216, v216, v39, v40
	v_max3_f32 v217, v217, v55, v56
	v_max3_f32 v216, v216, v41, v42
	v_max3_f32 v217, v217, v57, v58
	v_max3_f32 v216, v216, v43, v44
	v_max3_f32 v217, v217, v59, v60
	v_max3_f32 v216, v216, v45, v46
	v_max3_f32 v217, v217, v61, v62
	v_max3_f32 v216, v216, v47, v48
	v_max3_f32 v217, v217, v63, v64
	v_max_f32_e32 v216, v216, v49
	v_max_f32_e32 v217, v217, v65
	v_max_f32_e32 v216, v216, v217
	v_cmp_lt_f32_e32 vcc, 4.0, v216
	s_cbranch_vccz .Lna_nr_wcs
	v_mov_b32_e32 v217, v216
	s_nop 1
	v_permlane32_swap_b32_e32 v216, v217
	v_max_f32_e32 v215, v216, v217
	s_nop 15
	v_max_f32_e32 v216, v215, v220
	v_exp_f32_e64 v217, -v216
	v_add_f32_e32 v212, v212, v216
	v_and_b32_e32 v217, v217, v221
	v_sub_f32_e32 v34, v34, v216
	v_sub_f32_e32 v35, v35, v216
	v_sub_f32_e32 v36, v36, v216
	v_sub_f32_e32 v37, v37, v216
	v_sub_f32_e32 v38, v38, v216
	v_sub_f32_e32 v39, v39, v216
	v_sub_f32_e32 v40, v40, v216
	v_sub_f32_e32 v41, v41, v216
	v_sub_f32_e32 v42, v42, v216
	v_sub_f32_e32 v43, v43, v216
	v_sub_f32_e32 v44, v44, v216
	v_sub_f32_e32 v45, v45, v216
	v_sub_f32_e32 v46, v46, v216
	v_sub_f32_e32 v47, v47, v216
	v_sub_f32_e32 v48, v48, v216
	v_sub_f32_e32 v49, v49, v216
	v_sub_f32_e32 v50, v50, v216
	v_sub_f32_e32 v51, v51, v216
	v_sub_f32_e32 v52, v52, v216
	v_sub_f32_e32 v53, v53, v216
	v_sub_f32_e32 v54, v54, v216
	v_sub_f32_e32 v55, v55, v216
	v_sub_f32_e32 v56, v56, v216
	v_sub_f32_e32 v57, v57, v216
	v_sub_f32_e32 v58, v58, v216
	v_sub_f32_e32 v59, v59, v216
	v_sub_f32_e32 v60, v60, v216
	v_sub_f32_e32 v61, v61, v216
	v_sub_f32_e32 v62, v62, v216
	v_sub_f32_e32 v63, v63, v216
	v_sub_f32_e32 v64, v64, v216
	v_sub_f32_e32 v65, v65, v216
	v_sub_f32_e32 v114, v114, v216
	v_sub_f32_e32 v115, v115, v216
	v_sub_f32_e32 v116, v116, v216
	v_sub_f32_e32 v117, v117, v216
	v_sub_f32_e32 v118, v118, v216
	v_sub_f32_e32 v119, v119, v216
	v_sub_f32_e32 v120, v120, v216
	v_sub_f32_e32 v121, v121, v216
	v_sub_f32_e32 v122, v122, v216
	v_sub_f32_e32 v123, v123, v216
	v_sub_f32_e32 v124, v124, v216
	v_sub_f32_e32 v125, v125, v216
	v_sub_f32_e32 v126, v126, v216
	v_sub_f32_e32 v127, v127, v216
	v_sub_f32_e32 v128, v128, v216
	v_sub_f32_e32 v129, v129, v216
	v_sub_f32_e32 v130, v130, v216
	v_sub_f32_e32 v131, v131, v216
	v_sub_f32_e32 v132, v132, v216
	v_sub_f32_e32 v133, v133, v216
	v_sub_f32_e32 v134, v134, v216
	v_sub_f32_e32 v135, v135, v216
	v_sub_f32_e32 v136, v136, v216
	v_sub_f32_e32 v137, v137, v216
	v_sub_f32_e32 v138, v138, v216
	v_sub_f32_e32 v139, v139, v216
	v_sub_f32_e32 v140, v140, v216
	v_sub_f32_e32 v141, v141, v216
	v_sub_f32_e32 v142, v142, v216
	v_sub_f32_e32 v143, v143, v216
	v_sub_f32_e32 v144, v144, v216
	v_sub_f32_e32 v145, v145, v216
	v_mul_f32_e32 v213, v213, v217
	v_mul_f32_e32 v214, v214, v217
	v_mul_f32_e32 v2, v2, v217
	v_mul_f32_e32 v3, v3, v217
	v_mul_f32_e32 v4, v4, v217
	v_mul_f32_e32 v5, v5, v217
	v_mul_f32_e32 v6, v6, v217
	v_mul_f32_e32 v7, v7, v217
	v_mul_f32_e32 v8, v8, v217
	v_mul_f32_e32 v9, v9, v217
	v_mul_f32_e32 v10, v10, v217
	v_mul_f32_e32 v11, v11, v217
	v_mul_f32_e32 v12, v12, v217
	v_mul_f32_e32 v13, v13, v217
	v_mul_f32_e32 v14, v14, v217
	v_mul_f32_e32 v15, v15, v217
	v_mul_f32_e32 v16, v16, v217
	v_mul_f32_e32 v17, v17, v217
	v_mul_f32_e32 v18, v18, v217
	v_mul_f32_e32 v19, v19, v217
	v_mul_f32_e32 v20, v20, v217
	v_mul_f32_e32 v21, v21, v217
	v_mul_f32_e32 v22, v22, v217
	v_mul_f32_e32 v23, v23, v217
	v_mul_f32_e32 v24, v24, v217
	v_mul_f32_e32 v25, v25, v217
	v_mul_f32_e32 v26, v26, v217
	v_mul_f32_e32 v27, v27, v217
	v_mul_f32_e32 v28, v28, v217
	v_mul_f32_e32 v29, v29, v217
	v_mul_f32_e32 v30, v30, v217
	v_mul_f32_e32 v31, v31, v217
	v_mul_f32_e32 v32, v32, v217
	v_mul_f32_e32 v33, v33, v217

.Lna_done_wc:
	ds_read_b128 v[146:149], v200 offset:9216
	ds_read_b128 v[150:153], v200 offset:13824
	ds_read_b128 v[154:157], v200 offset:9248
	ds_read_b128 v[158:161], v200 offset:13856
	v_exp_f32_e32 v34, v34
	v_exp_f32_e32 v35, v35
	v_exp_f32_e32 v36, v36
	v_exp_f32_e32 v37, v37
	s_waitcnt lgkmcnt(2)
	v_mfma_f32_32x32x16_bf16 v[66:81], v[146:149], v[98:101], v[114:129]
	ds_read_b128 v[146:149], v200 offset:9280
	v_add_f32_e32 v213, v213, v34
	v_add_f32_e32 v214, v214, v35
	v_add_f32_e32 v213, v213, v36
	v_add_f32_e32 v214, v214, v37
	v_exp_f32_e32 v38, v38
	v_exp_f32_e32 v39, v39
	v_mfma_f32_32x32x16_bf16 v[82:97], v[150:153], v[98:101], v[130:145]
	ds_read_b128 v[150:153], v200 offset:13888
	v_exp_f32_e32 v40, v40
	v_exp_f32_e32 v41, v41
	v_add_f32_e32 v213, v213, v38
	v_add_f32_e32 v214, v214, v39
	v_add_f32_e32 v213, v213, v40
	s_waitcnt lgkmcnt(2)
	v_mfma_f32_32x32x16_bf16 v[66:81], v[154:157], v[102:105], v[66:81]
	ds_read_b128 v[154:157], v200 offset:9312
	v_add_f32_e32 v214, v214, v41
	v_cvt_pk_bf16_f32 v34, v34, v35
	v_cvt_pk_bf16_f32 v35, v36, v37
	v_cvt_pk_bf16_f32 v36, v38, v39
	v_cvt_pk_bf16_f32 v37, v40, v41
	v_exp_f32_e32 v42, v42
	v_exp_f32_e32 v43, v43
	v_mfma_f32_32x32x16_bf16 v[82:97], v[158:161], v[102:105], v[82:97]
	ds_read_b128 v[158:161], v200 offset:13920
	v_exp_f32_e32 v44, v44
	v_exp_f32_e32 v45, v45
	v_add_f32_e32 v213, v213, v42
	v_add_f32_e32 v214, v214, v43
	v_add_f32_e32 v213, v213, v44
	s_waitcnt lgkmcnt(2)
	v_mfma_f32_32x32x16_bf16 v[66:81], v[146:149], v[106:109], v[66:81]
	ds_read_b64 v[162:163], v202 offset:0
	ds_read_b64 v[164:165], v202 offset:16
	v_add_f32_e32 v214, v214, v45
	v_exp_f32_e32 v46, v46
	v_exp_f32_e32 v47, v47
	v_exp_f32_e32 v48, v48
	v_mfma_f32_32x32x16_bf16 v[82:97], v[150:153], v[106:109], v[82:97]
	ds_read_b64 v[166:167], v202 offset:4352
	ds_read_b64 v[168:169], v202 offset:4368
	v_exp_f32_e32 v49, v49
	v_add_f32_e32 v213, v213, v46
	v_add_f32_e32 v214, v214, v47
	v_add_f32_e32 v213, v213, v48
	v_add_f32_e32 v214, v214, v49
	v_cvt_pk_bf16_f32 v42, v42, v43
	v_cvt_pk_bf16_f32 v43, v44, v45
	s_waitcnt lgkmcnt(4)
	v_mfma_f32_32x32x16_bf16 v[66:81], v[154:157], v[110:113], v[66:81]
	ds_read_b64 v[170:171], v202 offset:32
	ds_read_b64 v[172:173], v202 offset:48
	v_cvt_pk_bf16_f32 v44, v46, v47
	v_cvt_pk_bf16_f32 v45, v48, v49
	v_exp_f32_e32 v50, v50
	v_exp_f32_e32 v51, v51
	v_exp_f32_e32 v52, v52
	v_mfma_f32_32x32x16_bf16 v[82:97], v[158:161], v[110:113], v[82:97]
	ds_read_b64 v[174:175], v202 offset:4384
	ds_read_b64 v[176:177], v202 offset:4400
	v_exp_f32_e32 v53, v53
	v_add_f32_e32 v213, v213, v50
	v_add_f32_e32 v214, v214, v51
	v_add_f32_e32 v213, v213, v52
	v_add_f32_e32 v214, v214, v53
	v_exp_f32_e32 v54, v54
	s_waitcnt lgkmcnt(6)
	v_mfma_f32_32x32x16_bf16 v[2:17], v[162:165], v[34:37], v[2:17]
	ds_read_b64 v[162:163], v202 offset:64
	ds_read_b64 v[164:165], v202 offset:80
	v_exp_f32_e32 v55, v55
	v_exp_f32_e32 v56, v56
	v_exp_f32_e32 v57, v57
	v_add_f32_e32 v213, v213, v54
	s_waitcnt lgkmcnt(6)
	v_mfma_f32_32x32x16_bf16 v[18:33], v[166:169], v[34:37], v[18:33]
	ds_read_b64 v[166:167], v202 offset:4416
	ds_read_b64 v[168:169], v202 offset:4432
	v_add_f32_e32 v214, v214, v55
	v_add_f32_e32 v213, v213, v56
	v_add_f32_e32 v214, v214, v57
	v_cvt_pk_bf16_f32 v50, v50, v51
	v_cvt_pk_bf16_f32 v51, v52, v53
	v_cvt_pk_bf16_f32 v52, v54, v55
	v_cvt_pk_bf16_f32 v53, v56, v57
	v_exp_f32_e32 v58, v58
	s_waitcnt lgkmcnt(6)
	v_mfma_f32_32x32x16_bf16 v[2:17], v[170:173], v[42:45], v[2:17]
	ds_read_b64 v[170:171], v202 offset:96
	ds_read_b64 v[172:173], v202 offset:112
	v_exp_f32_e32 v59, v59
	v_exp_f32_e32 v60, v60
	v_exp_f32_e32 v61, v61
	s_waitcnt lgkmcnt(6)
	v_mfma_f32_32x32x16_bf16 v[18:33], v[174:177], v[42:45], v[18:33]
	ds_read_b64 v[174:175], v202 offset:4448
	ds_read_b64 v[176:177], v202 offset:4464
	s_waitcnt vmcnt(2)
	ds_write_b128 v204, v[188:191] offset:0
	ds_write_b64 v205, v[192:193] offset:8704
	ds_write_b64 v205, v[194:195] offset:8712
	global_load_dwordx4 v[192:195], v207, s[14:15]
	s_add_u32 s14, s14, 0x80
	s_addc_u32 s15, s15, 0
	v_add_f32_e32 v213, v213, v58
	v_add_f32_e32 v214, v214, v59
	v_add_f32_e32 v213, v213, v60
	v_add_f32_e32 v214, v214, v61
	v_exp_f32_e32 v62, v62
	v_exp_f32_e32 v63, v63
	s_waitcnt lgkmcnt(9)
	v_mfma_f32_32x32x16_bf16 v[2:17], v[162:165], v[50:53], v[2:17]
	v_exp_f32_e32 v64, v64
	v_exp_f32_e32 v65, v65
	v_add_f32_e32 v213, v213, v62
	v_add_f32_e32 v214, v214, v63
	v_add_f32_e32 v213, v213, v64
	v_add_f32_e32 v214, v214, v65
	s_waitcnt lgkmcnt(7)
	v_mfma_f32_32x32x16_bf16 v[18:33], v[166:169], v[50:53], v[18:33]
	v_cvt_pk_bf16_f32 v58, v58, v59
	v_cvt_pk_bf16_f32 v59, v60, v61
	v_cvt_pk_bf16_f32 v60, v62, v63
	v_cvt_pk_bf16_f32 v61, v64, v65
	v_max3_f32 v216, v66, v67, v68
	v_max3_f32 v217, v82, v83, v84
	v_max3_f32 v216, v216, v69, v70
	s_waitcnt lgkmcnt(5)
	v_mfma_f32_32x32x16_bf16 v[2:17], v[170:173], v[58:61], v[2:17]
	v_max3_f32 v217, v217, v85, v86
	v_max3_f32 v216, v216, v71, v72
	v_max3_f32 v217, v217, v87, v88
	v_max3_f32 v216, v216, v73, v74
	v_max3_f32 v217, v217, v89, v90
	v_max3_f32 v216, v216, v75, v76
	v_max3_f32 v217, v217, v91, v92
	v_max3_f32 v216, v216, v77, v78
	s_waitcnt lgkmcnt(3)
	v_mfma_f32_32x32x16_bf16 v[18:33], v[174:177], v[58:61], v[18:33]
	v_max3_f32 v217, v217, v93, v94
	v_max3_f32 v216, v216, v79, v80
	v_max3_f32 v217, v217, v95, v96
	v_max_f32_e32 v216, v216, v81
	v_max_f32_e32 v217, v217, v97
	v_max_f32_e32 v216, v216, v217
	v_cmp_lt_f32_e32 vcc, 4.0, v216
	s_cbranch_vccz .Lna_nr_c0
	v_mov_b32_e32 v217, v216
	s_nop 1
	v_permlane32_swap_b32_e32 v216, v217
	v_max_f32_e32 v215, v216, v217
	s_nop 15
	v_max_f32_e32 v216, v215, v220
	v_exp_f32_e64 v217, -v216
	v_add_f32_e32 v212, v212, v216
	v_and_b32_e32 v217, v217, v221
	v_sub_f32_e32 v66, v66, v216
	v_sub_f32_e32 v67, v67, v216
	v_sub_f32_e32 v68, v68, v216
	v_sub_f32_e32 v69, v69, v216
	v_sub_f32_e32 v70, v70, v216
	v_sub_f32_e32 v71, v71, v216
	v_sub_f32_e32 v72, v72, v216
	v_sub_f32_e32 v73, v73, v216
	v_sub_f32_e32 v74, v74, v216
	v_sub_f32_e32 v75, v75, v216
	v_sub_f32_e32 v76, v76, v216
	v_sub_f32_e32 v77, v77, v216
	v_sub_f32_e32 v78, v78, v216
	v_sub_f32_e32 v79, v79, v216
	v_sub_f32_e32 v80, v80, v216
	v_sub_f32_e32 v81, v81, v216
	v_sub_f32_e32 v82, v82, v216
	v_sub_f32_e32 v83, v83, v216
	v_sub_f32_e32 v84, v84, v216
	v_sub_f32_e32 v85, v85, v216
	v_sub_f32_e32 v86, v86, v216
	v_sub_f32_e32 v87, v87, v216
	v_sub_f32_e32 v88, v88, v216
	v_sub_f32_e32 v89, v89, v216
	v_sub_f32_e32 v90, v90, v216
	v_sub_f32_e32 v91, v91, v216
	v_sub_f32_e32 v92, v92, v216
	v_sub_f32_e32 v93, v93, v216
	v_sub_f32_e32 v94, v94, v216
	v_sub_f32_e32 v95, v95, v216
	v_sub_f32_e32 v96, v96, v216
	v_sub_f32_e32 v97, v97, v216
	v_sub_f32_e32 v114, v114, v216
	v_sub_f32_e32 v115, v115, v216
	v_sub_f32_e32 v116, v116, v216
	v_sub_f32_e32 v117, v117, v216
	v_sub_f32_e32 v118, v118, v216
	v_sub_f32_e32 v119, v119, v216
	v_sub_f32_e32 v120, v120, v216
	v_sub_f32_e32 v121, v121, v216
	v_sub_f32_e32 v122, v122, v216
	v_sub_f32_e32 v123, v123, v216
	v_sub_f32_e32 v124, v124, v216
	v_sub_f32_e32 v125, v125, v216
	v_sub_f32_e32 v126, v126, v216
	v_sub_f32_e32 v127, v127, v216
	v_sub_f32_e32 v128, v128, v216
	v_sub_f32_e32 v129, v129, v216
	v_sub_f32_e32 v130, v130, v216
	v_sub_f32_e32 v131, v131, v216
	v_sub_f32_e32 v132, v132, v216
	v_sub_f32_e32 v133, v133, v216
	v_sub_f32_e32 v134, v134, v216
	v_sub_f32_e32 v135, v135, v216
	v_sub_f32_e32 v136, v136, v216
	v_sub_f32_e32 v137, v137, v216
	v_sub_f32_e32 v138, v138, v216
	v_sub_f32_e32 v139, v139, v216
	v_sub_f32_e32 v140, v140, v216
	v_sub_f32_e32 v141, v141, v216
	v_sub_f32_e32 v142, v142, v216
	v_sub_f32_e32 v143, v143, v216
	v_sub_f32_e32 v144, v144, v216
	v_sub_f32_e32 v145, v145, v216
	v_mul_f32_e32 v213, v213, v217
	v_mul_f32_e32 v214, v214, v217
	v_mul_f32_e32 v2, v2, v217
	v_mul_f32_e32 v3, v3, v217
	v_mul_f32_e32 v4, v4, v217
	v_mul_f32_e32 v5, v5, v217
	v_mul_f32_e32 v6, v6, v217
	v_mul_f32_e32 v7, v7, v217
	v_mul_f32_e32 v8, v8, v217
	v_mul_f32_e32 v9, v9, v217
	v_mul_f32_e32 v10, v10, v217
	v_mul_f32_e32 v11, v11, v217
	v_mul_f32_e32 v12, v12, v217
	v_mul_f32_e32 v13, v13, v217
	v_mul_f32_e32 v14, v14, v217
	v_mul_f32_e32 v15, v15, v217
	v_mul_f32_e32 v16, v16, v217
	v_mul_f32_e32 v17, v17, v217
	v_mul_f32_e32 v18, v18, v217
	v_mul_f32_e32 v19, v19, v217
	v_mul_f32_e32 v20, v20, v217
	v_mul_f32_e32 v21, v21, v217
	v_mul_f32_e32 v22, v22, v217
	v_mul_f32_e32 v23, v23, v217
	v_mul_f32_e32 v24, v24, v217
	v_mul_f32_e32 v25, v25, v217
	v_mul_f32_e32 v26, v26, v217
	v_mul_f32_e32 v27, v27, v217
	v_mul_f32_e32 v28, v28, v217
	v_mul_f32_e32 v29, v29, v217
	v_mul_f32_e32 v30, v30, v217
	v_mul_f32_e32 v31, v31, v217
	v_mul_f32_e32 v32, v32, v217
	v_mul_f32_e32 v33, v33, v217
.Lna_nr_c0:
	s_waitcnt lgkmcnt(0)
	s_barrier
	ds_read_b128 v[146:149], v200 offset:0
	ds_read_b128 v[150:153], v200 offset:4608
	ds_read_b128 v[154:157], v200 offset:32
	ds_read_b128 v[158:161], v200 offset:4640
	v_exp_f32_e32 v66, v66
	v_exp_f32_e32 v67, v67
	v_exp_f32_e32 v68, v68
	v_exp_f32_e32 v69, v69
	s_waitcnt lgkmcnt(2)
	v_mfma_f32_32x32x16_bf16 v[34:49], v[146:149], v[98:101], v[114:129]
	ds_read_b128 v[146:149], v200 offset:64
	v_add_f32_e32 v213, v213, v66
	v_add_f32_e32 v214, v214, v67
	v_add_f32_e32 v213, v213, v68
	v_add_f32_e32 v214, v214, v69
	v_exp_f32_e32 v70, v70
	v_exp_f32_e32 v71, v71
	v_mfma_f32_32x32x16_bf16 v[50:65], v[150:153], v[98:101], v[130:145]
	ds_read_b128 v[150:153], v200 offset:4672
	v_exp_f32_e32 v72, v72
	v_exp_f32_e32 v73, v73
	v_add_f32_e32 v213, v213, v70
	v_add_f32_e32 v214, v214, v71
	v_add_f32_e32 v213, v213, v72
	s_waitcnt lgkmcnt(2)
	v_mfma_f32_32x32x16_bf16 v[34:49], v[154:157], v[102:105], v[34:49]
	ds_read_b128 v[154:157], v200 offset:96
	v_add_f32_e32 v214, v214, v73
	v_cvt_pk_bf16_f32 v66, v66, v67
	v_cvt_pk_bf16_f32 v67, v68, v69
	v_cvt_pk_bf16_f32 v68, v70, v71
	v_cvt_pk_bf16_f32 v69, v72, v73
	v_exp_f32_e32 v74, v74
	v_exp_f32_e32 v75, v75
	v_mfma_f32_32x32x16_bf16 v[50:65], v[158:161], v[102:105], v[50:65]
	ds_read_b128 v[158:161], v200 offset:4704
	v_exp_f32_e32 v76, v76
	v_exp_f32_e32 v77, v77
	v_add_f32_e32 v213, v213, v74
	v_add_f32_e32 v214, v214, v75
	v_add_f32_e32 v213, v213, v76
	s_waitcnt lgkmcnt(2)
	v_mfma_f32_32x32x16_bf16 v[34:49], v[146:149], v[106:109], v[34:49]
	ds_read_b64 v[162:163], v202 offset:8704
	ds_read_b64 v[164:165], v202 offset:8720
	v_add_f32_e32 v214, v214, v77
	v_exp_f32_e32 v78, v78
	v_exp_f32_e32 v79, v79
	v_exp_f32_e32 v80, v80
	v_mfma_f32_32x32x16_bf16 v[50:65], v[150:153], v[106:109], v[50:65]
	ds_read_b64 v[166:167], v202 offset:13056
	ds_read_b64 v[168:169], v202 offset:13072
	v_exp_f32_e32 v81, v81
	v_add_f32_e32 v213, v213, v78
	v_add_f32_e32 v214, v214, v79
	v_add_f32_e32 v213, v213, v80
	v_add_f32_e32 v214, v214, v81
	v_cvt_pk_bf16_f32 v74, v74, v75
	v_cvt_pk_bf16_f32 v75, v76, v77
	s_waitcnt lgkmcnt(4)
	v_mfma_f32_32x32x16_bf16 v[34:49], v[154:157], v[110:113], v[34:49]
	ds_read_b64 v[170:171], v202 offset:8736
	ds_read_b64 v[172:173], v202 offset:8752
	v_cvt_pk_bf16_f32 v76, v78, v79
	v_cvt_pk_bf16_f32 v77, v80, v81
	v_exp_f32_e32 v82, v82
	v_exp_f32_e32 v83, v83
	v_exp_f32_e32 v84, v84
	v_mfma_f32_32x32x16_bf16 v[50:65], v[158:161], v[110:113], v[50:65]
	ds_read_b64 v[174:175], v202 offset:13088
	ds_read_b64 v[176:177], v202 offset:13104
	v_exp_f32_e32 v85, v85
	v_add_f32_e32 v213, v213, v82
	v_add_f32_e32 v214, v214, v83
	v_add_f32_e32 v213, v213, v84
	v_add_f32_e32 v214, v214, v85
	v_exp_f32_e32 v86, v86
	s_waitcnt lgkmcnt(6)
	v_mfma_f32_32x32x16_bf16 v[2:17], v[162:165], v[66:69], v[2:17]
	ds_read_b64 v[162:163], v202 offset:8768
	ds_read_b64 v[164:165], v202 offset:8784
	v_exp_f32_e32 v87, v87
	v_exp_f32_e32 v88, v88
	v_exp_f32_e32 v89, v89
	v_add_f32_e32 v213, v213, v86
	s_waitcnt lgkmcnt(6)
	v_mfma_f32_32x32x16_bf16 v[18:33], v[166:169], v[66:69], v[18:33]
	ds_read_b64 v[166:167], v202 offset:13120
	ds_read_b64 v[168:169], v202 offset:13136
	v_add_f32_e32 v214, v214, v87
	v_add_f32_e32 v213, v213, v88
	v_add_f32_e32 v214, v214, v89
	v_cvt_pk_bf16_f32 v82, v82, v83
	v_cvt_pk_bf16_f32 v83, v84, v85
	v_cvt_pk_bf16_f32 v84, v86, v87
	v_cvt_pk_bf16_f32 v85, v88, v89
	v_exp_f32_e32 v90, v90
	s_waitcnt lgkmcnt(6)
	v_mfma_f32_32x32x16_bf16 v[2:17], v[170:173], v[74:77], v[2:17]
	ds_read_b64 v[170:171], v202 offset:8800
	ds_read_b64 v[172:173], v202 offset:8816
	v_exp_f32_e32 v91, v91
	v_exp_f32_e32 v92, v92
	v_exp_f32_e32 v93, v93
	s_waitcnt lgkmcnt(6)
	v_mfma_f32_32x32x16_bf16 v[18:33], v[174:177], v[74:77], v[18:33]
	ds_read_b64 v[174:175], v202 offset:13152
	ds_read_b64 v[176:177], v202 offset:13168
	s_waitcnt vmcnt(1)
	ds_write_b128 v204, v[230:233] offset:9216
	ds_write_b64 v205, v[234:235] offset:0
	ds_write_b64 v205, v[236:237] offset:8
	v_add_f32_e32 v213, v213, v90
	v_add_f32_e32 v214, v214, v91
	v_add_f32_e32 v213, v213, v92
	v_add_f32_e32 v214, v214, v93
	v_exp_f32_e32 v94, v94
	v_exp_f32_e32 v95, v95
	s_waitcnt lgkmcnt(9)
	v_mfma_f32_32x32x16_bf16 v[2:17], v[162:165], v[82:85], v[2:17]
	v_exp_f32_e32 v96, v96
	v_exp_f32_e32 v97, v97
	v_add_f32_e32 v213, v213, v94
	v_add_f32_e32 v214, v214, v95
	v_add_f32_e32 v213, v213, v96
	v_add_f32_e32 v214, v214, v97
	s_waitcnt lgkmcnt(7)
	v_mfma_f32_32x32x16_bf16 v[18:33], v[166:169], v[82:85], v[18:33]
	v_cvt_pk_bf16_f32 v90, v90, v91
	v_cvt_pk_bf16_f32 v91, v92, v93
	v_cvt_pk_bf16_f32 v92, v94, v95
	v_cvt_pk_bf16_f32 v93, v96, v97
	v_max3_f32 v216, v34, v35, v36
	v_max3_f32 v217, v50, v51, v52
	v_max3_f32 v216, v216, v37, v38
	s_waitcnt lgkmcnt(5)
	v_mfma_f32_32x32x16_bf16 v[2:17], v[170:173], v[90:93], v[2:17]
	v_max3_f32 v217, v217, v53, v54
	v_max3_f32 v216, v216, v39, v40
	v_max3_f32 v217, v217, v55, v56
	v_max3_f32 v216, v216, v41, v42
	v_max3_f32 v217, v217, v57, v58
	v_max3_f32 v216, v216, v43, v44
	v_max3_f32 v217, v217, v59, v60
	v_max3_f32 v216, v216, v45, v46
	s_waitcnt lgkmcnt(3)
	v_mfma_f32_32x32x16_bf16 v[18:33], v[174:177], v[90:93], v[18:33]
	v_max3_f32 v217, v217, v61, v62
	v_max3_f32 v216, v216, v47, v48
	v_max3_f32 v217, v217, v63, v64
	v_max_f32_e32 v216, v216, v49
	v_max_f32_e32 v217, v217, v65
	v_max_f32_e32 v216, v216, v217
	v_cmp_lt_f32_e32 vcc, 4.0, v216
	s_cbranch_vccz .Lna_nr_c1
	v_mov_b32_e32 v217, v216
	s_nop 1
	v_permlane32_swap_b32_e32 v216, v217
	v_max_f32_e32 v215, v216, v217
	s_nop 15
	v_max_f32_e32 v216, v215, v220
	v_exp_f32_e64 v217, -v216
	v_add_f32_e32 v212, v212, v216
	v_and_b32_e32 v217, v217, v221
	v_sub_f32_e32 v34, v34, v216
	v_sub_f32_e32 v35, v35, v216
	v_sub_f32_e32 v36, v36, v216
	v_sub_f32_e32 v37, v37, v216
	v_sub_f32_e32 v38, v38, v216
	v_sub_f32_e32 v39, v39, v216
	v_sub_f32_e32 v40, v40, v216
	v_sub_f32_e32 v41, v41, v216
	v_sub_f32_e32 v42, v42, v216
	v_sub_f32_e32 v43, v43, v216
	v_sub_f32_e32 v44, v44, v216
	v_sub_f32_e32 v45, v45, v216
	v_sub_f32_e32 v46, v46, v216
	v_sub_f32_e32 v47, v47, v216
	v_sub_f32_e32 v48, v48, v216
	v_sub_f32_e32 v49, v49, v216
	v_sub_f32_e32 v50, v50, v216
	v_sub_f32_e32 v51, v51, v216
	v_sub_f32_e32 v52, v52, v216
	v_sub_f32_e32 v53, v53, v216
	v_sub_f32_e32 v54, v54, v216
	v_sub_f32_e32 v55, v55, v216
	v_sub_f32_e32 v56, v56, v216
	v_sub_f32_e32 v57, v57, v216
	v_sub_f32_e32 v58, v58, v216
	v_sub_f32_e32 v59, v59, v216
	v_sub_f32_e32 v60, v60, v216
	v_sub_f32_e32 v61, v61, v216
	v_sub_f32_e32 v62, v62, v216
	v_sub_f32_e32 v63, v63, v216
	v_sub_f32_e32 v64, v64, v216
	v_sub_f32_e32 v65, v65, v216
	v_sub_f32_e32 v114, v114, v216
	v_sub_f32_e32 v115, v115, v216
	v_sub_f32_e32 v116, v116, v216
	v_sub_f32_e32 v117, v117, v216
	v_sub_f32_e32 v118, v118, v216
	v_sub_f32_e32 v119, v119, v216
	v_sub_f32_e32 v120, v120, v216
	v_sub_f32_e32 v121, v121, v216
	v_sub_f32_e32 v122, v122, v216
	v_sub_f32_e32 v123, v123, v216
	v_sub_f32_e32 v124, v124, v216
	v_sub_f32_e32 v125, v125, v216
	v_sub_f32_e32 v126, v126, v216
	v_sub_f32_e32 v127, v127, v216
	v_sub_f32_e32 v128, v128, v216
	v_sub_f32_e32 v129, v129, v216
	v_sub_f32_e32 v130, v130, v216
	v_sub_f32_e32 v131, v131, v216
	v_sub_f32_e32 v132, v132, v216
	v_sub_f32_e32 v133, v133, v216
	v_sub_f32_e32 v134, v134, v216
	v_sub_f32_e32 v135, v135, v216
	v_sub_f32_e32 v136, v136, v216
	v_sub_f32_e32 v137, v137, v216
	v_sub_f32_e32 v138, v138, v216
	v_sub_f32_e32 v139, v139, v216
	v_sub_f32_e32 v140, v140, v216
	v_sub_f32_e32 v141, v141, v216
	v_sub_f32_e32 v142, v142, v216
	v_sub_f32_e32 v143, v143, v216
	v_sub_f32_e32 v144, v144, v216
	v_sub_f32_e32 v145, v145, v216
	v_mul_f32_e32 v213, v213, v217
	v_mul_f32_e32 v214, v214, v217
	v_mul_f32_e32 v2, v2, v217
	v_mul_f32_e32 v3, v3, v217
	v_mul_f32_e32 v4, v4, v217
	v_mul_f32_e32 v5, v5, v217
	v_mul_f32_e32 v6, v6, v217
	v_mul_f32_e32 v7, v7, v217
	v_mul_f32_e32 v8, v8, v217
	v_mul_f32_e32 v9, v9, v217
	v_mul_f32_e32 v10, v10, v217
	v_mul_f32_e32 v11, v11, v217
	v_mul_f32_e32 v12, v12, v217
	v_mul_f32_e32 v13, v13, v217
	v_mul_f32_e32 v14, v14, v217
	v_mul_f32_e32 v15, v15, v217
	v_mul_f32_e32 v16, v16, v217
	v_mul_f32_e32 v17, v17, v217
	v_mul_f32_e32 v18, v18, v217
	v_mul_f32_e32 v19, v19, v217
	v_mul_f32_e32 v20, v20, v217
	v_mul_f32_e32 v21, v21, v217
	v_mul_f32_e32 v22, v22, v217
	v_mul_f32_e32 v23, v23, v217
	v_mul_f32_e32 v24, v24, v217
	v_mul_f32_e32 v25, v25, v217
	v_mul_f32_e32 v26, v26, v217
	v_mul_f32_e32 v27, v27, v217
	v_mul_f32_e32 v28, v28, v217
	v_mul_f32_e32 v29, v29, v217
	v_mul_f32_e32 v30, v30, v217
	v_mul_f32_e32 v31, v31, v217
	v_mul_f32_e32 v32, v32, v217
	v_mul_f32_e32 v33, v33, v217
.Lna_nr_c1:
	s_waitcnt lgkmcnt(0)
	s_barrier
	ds_read_b128 v[146:149], v200 offset:9216
	ds_read_b128 v[150:153], v200 offset:13824
	ds_read_b128 v[154:157], v200 offset:9248
	ds_read_b128 v[158:161], v200 offset:13856
	v_exp_f32_e32 v34, v34
	v_exp_f32_e32 v35, v35
	v_exp_f32_e32 v36, v36
	v_exp_f32_e32 v37, v37
	s_waitcnt lgkmcnt(2)
	v_mfma_f32_32x32x16_bf16 v[66:81], v[146:149], v[98:101], v[114:129]
	ds_read_b128 v[146:149], v200 offset:9280
	v_add_f32_e32 v213, v213, v34
	v_add_f32_e32 v214, v214, v35
	v_add_f32_e32 v213, v213, v36
	v_add_f32_e32 v214, v214, v37
	v_exp_f32_e32 v38, v38
	v_exp_f32_e32 v39, v39
	v_mfma_f32_32x32x16_bf16 v[82:97], v[150:153], v[98:101], v[130:145]
	ds_read_b128 v[150:153], v200 offset:13888
	v_exp_f32_e32 v40, v40
	v_exp_f32_e32 v41, v41
	v_add_f32_e32 v213, v213, v38
	v_add_f32_e32 v214, v214, v39
	v_add_f32_e32 v213, v213, v40
	s_waitcnt lgkmcnt(2)
	v_mfma_f32_32x32x16_bf16 v[66:81], v[154:157], v[102:105], v[66:81]
	ds_read_b128 v[154:157], v200 offset:9312
	v_add_f32_e32 v214, v214, v41
	v_cvt_pk_bf16_f32 v34, v34, v35
	v_cvt_pk_bf16_f32 v35, v36, v37
	v_cvt_pk_bf16_f32 v36, v38, v39
	v_cvt_pk_bf16_f32 v37, v40, v41
	v_exp_f32_e32 v42, v42
	v_exp_f32_e32 v43, v43
	v_mfma_f32_32x32x16_bf16 v[82:97], v[158:161], v[102:105], v[82:97]
	ds_read_b128 v[158:161], v200 offset:13920
	v_exp_f32_e32 v44, v44
	v_exp_f32_e32 v45, v45
	v_add_f32_e32 v213, v213, v42
	v_add_f32_e32 v214, v214, v43
	v_add_f32_e32 v213, v213, v44
	s_waitcnt lgkmcnt(2)
	v_mfma_f32_32x32x16_bf16 v[66:81], v[146:149], v[106:109], v[66:81]
	ds_read_b64 v[162:163], v202 offset:0
	ds_read_b64 v[164:165], v202 offset:16
	v_add_f32_e32 v214, v214, v45
	v_exp_f32_e32 v46, v46
	v_exp_f32_e32 v47, v47
	v_exp_f32_e32 v48, v48
	v_mfma_f32_32x32x16_bf16 v[82:97], v[150:153], v[106:109], v[82:97]
	ds_read_b64 v[166:167], v202 offset:4352
	ds_read_b64 v[168:169], v202 offset:4368
	v_exp_f32_e32 v49, v49
	v_add_f32_e32 v213, v213, v46
	v_add_f32_e32 v214, v214, v47
	v_add_f32_e32 v213, v213, v48
	v_add_f32_e32 v214, v214, v49
	v_cvt_pk_bf16_f32 v42, v42, v43
	v_cvt_pk_bf16_f32 v43, v44, v45
	s_waitcnt lgkmcnt(4)
	v_mfma_f32_32x32x16_bf16 v[66:81], v[154:157], v[110:113], v[66:81]
	ds_read_b64 v[170:171], v202 offset:32
	ds_read_b64 v[172:173], v202 offset:48
	v_cvt_pk_bf16_f32 v44, v46, v47
	v_cvt_pk_bf16_f32 v45, v48, v49
	v_exp_f32_e32 v50, v50
	v_exp_f32_e32 v51, v51
	v_exp_f32_e32 v52, v52
	v_mfma_f32_32x32x16_bf16 v[82:97], v[158:161], v[110:113], v[82:97]
	ds_read_b64 v[174:175], v202 offset:4384
	ds_read_b64 v[176:177], v202 offset:4400
	v_exp_f32_e32 v53, v53
	v_add_f32_e32 v213, v213, v50
	v_add_f32_e32 v214, v214, v51
	v_add_f32_e32 v213, v213, v52
	v_add_f32_e32 v214, v214, v53
	v_exp_f32_e32 v54, v54
	s_waitcnt lgkmcnt(6)
	v_mfma_f32_32x32x16_bf16 v[2:17], v[162:165], v[34:37], v[2:17]
	ds_read_b64 v[162:163], v202 offset:64
	ds_read_b64 v[164:165], v202 offset:80
	v_exp_f32_e32 v55, v55
	v_exp_f32_e32 v56, v56
	v_exp_f32_e32 v57, v57
	v_add_f32_e32 v213, v213, v54
	s_waitcnt lgkmcnt(6)
	v_mfma_f32_32x32x16_bf16 v[18:33], v[166:169], v[34:37], v[18:33]
	ds_read_b64 v[166:167], v202 offset:4416
	ds_read_b64 v[168:169], v202 offset:4432
	v_add_f32_e32 v214, v214, v55
	v_add_f32_e32 v213, v213, v56
	v_add_f32_e32 v214, v214, v57
	v_cvt_pk_bf16_f32 v50, v50, v51
	v_cvt_pk_bf16_f32 v51, v52, v53
	v_cvt_pk_bf16_f32 v52, v54, v55
	v_cvt_pk_bf16_f32 v53, v56, v57
	v_exp_f32_e32 v58, v58
	s_waitcnt lgkmcnt(6)
	v_mfma_f32_32x32x16_bf16 v[2:17], v[170:173], v[42:45], v[2:17]
	ds_read_b64 v[170:171], v202 offset:96
	ds_read_b64 v[172:173], v202 offset:112
	v_exp_f32_e32 v59, v59
	v_exp_f32_e32 v60, v60
	v_exp_f32_e32 v61, v61
	s_waitcnt lgkmcnt(6)
	v_mfma_f32_32x32x16_bf16 v[18:33], v[174:177], v[42:45], v[18:33]
	ds_read_b64 v[174:175], v202 offset:4448
	ds_read_b64 v[176:177], v202 offset:4464
	s_waitcnt vmcnt(0)
	ds_write_b64 v205, v[192:193] offset:8704
	ds_write_b64 v205, v[194:195] offset:8712
	v_add_f32_e32 v213, v213, v58
	v_add_f32_e32 v214, v214, v59
	v_add_f32_e32 v213, v213, v60
	v_add_f32_e32 v214, v214, v61
	v_exp_f32_e32 v62, v62
	v_exp_f32_e32 v63, v63
	s_waitcnt lgkmcnt(8)
	v_mfma_f32_32x32x16_bf16 v[2:17], v[162:165], v[50:53], v[2:17]
	v_exp_f32_e32 v64, v64
	v_exp_f32_e32 v65, v65
	v_add_f32_e32 v213, v213, v62
	v_add_f32_e32 v214, v214, v63
	v_add_f32_e32 v213, v213, v64
	v_add_f32_e32 v214, v214, v65
	s_waitcnt lgkmcnt(6)
	v_mfma_f32_32x32x16_bf16 v[18:33], v[166:169], v[50:53], v[18:33]
	v_cvt_pk_bf16_f32 v58, v58, v59
	v_cvt_pk_bf16_f32 v59, v60, v61
	v_cvt_pk_bf16_f32 v60, v62, v63
	v_cvt_pk_bf16_f32 v61, v64, v65
	v_max3_f32 v216, v66, v67, v68
	v_max3_f32 v217, v82, v83, v84
	v_max3_f32 v216, v216, v69, v70
	s_waitcnt lgkmcnt(4)
	v_mfma_f32_32x32x16_bf16 v[2:17], v[170:173], v[58:61], v[2:17]
	v_max3_f32 v217, v217, v85, v86
	v_max3_f32 v216, v216, v71, v72
	v_max3_f32 v217, v217, v87, v88
	v_max3_f32 v216, v216, v73, v74
	v_max3_f32 v217, v217, v89, v90
	v_max3_f32 v216, v216, v75, v76
	v_max3_f32 v217, v217, v91, v92
	v_max3_f32 v216, v216, v77, v78
	s_waitcnt lgkmcnt(2)
	v_mfma_f32_32x32x16_bf16 v[18:33], v[174:177], v[58:61], v[18:33]
	v_max3_f32 v217, v217, v93, v94
	v_max3_f32 v216, v216, v79, v80
	v_max3_f32 v217, v217, v95, v96
	v_max_f32_e32 v216, v216, v81
	v_max_f32_e32 v217, v217, v97
	v_max_f32_e32 v216, v216, v217
	v_cmp_lt_f32_e32 vcc, 4.0, v216
	s_cbranch_vccz .Lna_nr_c2
	v_mov_b32_e32 v217, v216
	s_nop 1
	v_permlane32_swap_b32_e32 v216, v217
	v_max_f32_e32 v215, v216, v217
	s_nop 15
	v_max_f32_e32 v216, v215, v220
	v_exp_f32_e64 v217, -v216
	v_add_f32_e32 v212, v212, v216
	v_and_b32_e32 v217, v217, v221
	v_sub_f32_e32 v66, v66, v216
	v_sub_f32_e32 v67, v67, v216
	v_sub_f32_e32 v68, v68, v216
	v_sub_f32_e32 v69, v69, v216
	v_sub_f32_e32 v70, v70, v216
	v_sub_f32_e32 v71, v71, v216
	v_sub_f32_e32 v72, v72, v216
	v_sub_f32_e32 v73, v73, v216
	v_sub_f32_e32 v74, v74, v216
	v_sub_f32_e32 v75, v75, v216
	v_sub_f32_e32 v76, v76, v216
	v_sub_f32_e32 v77, v77, v216
	v_sub_f32_e32 v78, v78, v216
	v_sub_f32_e32 v79, v79, v216
	v_sub_f32_e32 v80, v80, v216
	v_sub_f32_e32 v81, v81, v216
	v_sub_f32_e32 v82, v82, v216
	v_sub_f32_e32 v83, v83, v216
	v_sub_f32_e32 v84, v84, v216
	v_sub_f32_e32 v85, v85, v216
	v_sub_f32_e32 v86, v86, v216
	v_sub_f32_e32 v87, v87, v216
	v_sub_f32_e32 v88, v88, v216
	v_sub_f32_e32 v89, v89, v216
	v_sub_f32_e32 v90, v90, v216
	v_sub_f32_e32 v91, v91, v216
	v_sub_f32_e32 v92, v92, v216
	v_sub_f32_e32 v93, v93, v216
	v_sub_f32_e32 v94, v94, v216
	v_sub_f32_e32 v95, v95, v216
	v_sub_f32_e32 v96, v96, v216
	v_sub_f32_e32 v97, v97, v216
	v_sub_f32_e32 v114, v114, v216
	v_sub_f32_e32 v115, v115, v216
	v_sub_f32_e32 v116, v116, v216
	v_sub_f32_e32 v117, v117, v216
	v_sub_f32_e32 v118, v118, v216
	v_sub_f32_e32 v119, v119, v216
	v_sub_f32_e32 v120, v120, v216
	v_sub_f32_e32 v121, v121, v216
	v_sub_f32_e32 v122, v122, v216
	v_sub_f32_e32 v123, v123, v216
	v_sub_f32_e32 v124, v124, v216
	v_sub_f32_e32 v125, v125, v216
	v_sub_f32_e32 v126, v126, v216
	v_sub_f32_e32 v127, v127, v216
	v_sub_f32_e32 v128, v128, v216
	v_sub_f32_e32 v129, v129, v216
	v_sub_f32_e32 v130, v130, v216
	v_sub_f32_e32 v131, v131, v216
	v_sub_f32_e32 v132, v132, v216
	v_sub_f32_e32 v133, v133, v216
	v_sub_f32_e32 v134, v134, v216
	v_sub_f32_e32 v135, v135, v216
	v_sub_f32_e32 v136, v136, v216
	v_sub_f32_e32 v137, v137, v216
	v_sub_f32_e32 v138, v138, v216
	v_sub_f32_e32 v139, v139, v216
	v_sub_f32_e32 v140, v140, v216
	v_sub_f32_e32 v141, v141, v216
	v_sub_f32_e32 v142, v142, v216
	v_sub_f32_e32 v143, v143, v216
	v_sub_f32_e32 v144, v144, v216
	v_sub_f32_e32 v145, v145, v216
	v_mul_f32_e32 v213, v213, v217
	v_mul_f32_e32 v214, v214, v217
	v_mul_f32_e32 v2, v2, v217
	v_mul_f32_e32 v3, v3, v217
	v_mul_f32_e32 v4, v4, v217
	v_mul_f32_e32 v5, v5, v217
	v_mul_f32_e32 v6, v6, v217
	v_mul_f32_e32 v7, v7, v217
	v_mul_f32_e32 v8, v8, v217
	v_mul_f32_e32 v9, v9, v217
	v_mul_f32_e32 v10, v10, v217
	v_mul_f32_e32 v11, v11, v217
	v_mul_f32_e32 v12, v12, v217
	v_mul_f32_e32 v13, v13, v217
	v_mul_f32_e32 v14, v14, v217
	v_mul_f32_e32 v15, v15, v217
	v_mul_f32_e32 v16, v16, v217
	v_mul_f32_e32 v17, v17, v217
	v_mul_f32_e32 v18, v18, v217
	v_mul_f32_e32 v19, v19, v217
	v_mul_f32_e32 v20, v20, v217
	v_mul_f32_e32 v21, v21, v217
	v_mul_f32_e32 v22, v22, v217
	v_mul_f32_e32 v23, v23, v217
	v_mul_f32_e32 v24, v24, v217
	v_mul_f32_e32 v25, v25, v217
	v_mul_f32_e32 v26, v26, v217
	v_mul_f32_e32 v27, v27, v217
	v_mul_f32_e32 v28, v28, v217
	v_mul_f32_e32 v29, v29, v217
	v_mul_f32_e32 v30, v30, v217
	v_mul_f32_e32 v31, v31, v217
	v_mul_f32_e32 v32, v32, v217
	v_mul_f32_e32 v33, v33, v217
